# v19 + back-edge rotation of the six GEMM K-loops (counter/pointer updates and exit test ahead of the loop-back barrier)
# baseline (speedup 1.0000x reference)
; #define PG8_STAGE(bufoff, gbase, voff) do { _Pragma("unroll") for (int _i = 0; _i < 2; ++_i) \
;         __builtin_amdgcn_global_load_lds((const unsigned*)((const char*)(gbase) + (voff)[_i]), (LAS unsigned*)(lds + (bufoff) + ldsw + _i * 8192), 16, 0, 0); } while (0)
; #define PG8_LDA(dst, b, h) do { _Pragma("unroll") for (int m = 0; m < 4; ++m) _Pragma("unroll") for (int k = 0; k < 2; ++k) dst[m][k] = *(const LAS bf16x8*)(lds + PG8_SA(b, h) + aoff + m * 2048 + k * 1024); } while (0)
; #define PG8_LDB(dst, b, h) do { _Pragma("unroll") for (int n = 0; n < 2; ++n) _Pragma("unroll") for (int k = 0; k < 2; ++k) dst[n][k] = *(const LAS bf16x8*)(lds + PG8_SB(b, h) + boff + n * 2048 + k * 1024); } while (0)
; #define PG8_MMA(ai, bj, At, Bt) do { __builtin_amdgcn_s_setprio(1); _Pragma("unroll") for (int m = 0; m < 4; ++m) _Pragma("unroll") for (int n = 0; n < 2; ++n) _Pragma("unroll") for (int k = 0; k < 2; ++k) \
;         acc[ai][bj][m][n] = __builtin_amdgcn_mfma_f32_16x16x32_bf16(Bt[n][k], At[m][k], acc[ai][bj][m][n], 0, 0, 0); __builtin_amdgcn_s_setprio(0); } while (0)
; #define PG8_WAIT_V(n) asm volatile("s_waitcnt vmcnt(" #n ")" ::: "memory")
; #define PG8_WAIT_L(n) asm volatile("s_waitcnt lgkmcnt(" #n ")" ::: "memory")
; #define PG8_BAR __builtin_amdgcn_s_barrier()
; template <class Epi, bool ALIGN_EPI = false, bool SP2 = true>
; __device__ __forceinline__ void gemm_phase(LAS unsigned char* lds, const Gemm g, const StaticOrder& S, const Epi& E) {
;     ...
;         for (int t = 0; t < nt; t += 2) {
;             const bool last = (t == nt - 2);
;             const char* a1 = cA + (size_t)(t + 1) * kstep;
;             const char* a2 = last ? nA : cA + (size_t)(t + 2) * kstep; const char* b2 = last ? nB : cB + (size_t)(t + 2) * kstep;
;             const char* a3 = a2 + kstep; const char* b3 = b2 + kstep;
;             if constexpr (SP2) {
;             PG8_LDB(B0, 0, 0); PG8_LDB(B1, 0, 1); PG8_SCHED; PG8_LDA(At, 0, 0); PG8_STAGE(PG8_SA(1, 1), a1 + hstep, voffA);
;             PG8_WAIT_V(8); PG8_WAIT_L(0); PG8_BAR; PG8_MMA(0, 0, At, B0); PG8_MMA(0, 1, At, B1); PG8_BAR; PG8_SCHED;
;             PG8_LDA(At, 0, 1); PG8_STAGE(PG8_SB(0, 0), b2, voffB); PG8_STAGE(PG8_SB(0, 1), b2 + hstep, voffB); PG8_STAGE(PG8_SA(0, 0), a2, voffA);
;             PG8_WAIT_V(8); PG8_WAIT_L(0); PG8_BAR; PG8_MMA(1, 0, At, B0); PG8_MMA(1, 1, At, B1); PG8_BAR; PG8_SCHED;
.LBB0_155:
	ds_read_b128 v[146:149], v157
	s_waitcnt lgkmcnt(0)
	ds_read_b128 v[150:153], v157 offset:1024
	ds_read_b128 v[166:169], v157 offset:2048
	ds_read_b128 v[170:173], v157 offset:3072
	ds_read_b128 v[174:177], v158
	ds_read_b128 v[178:181], v158 offset:1024
	ds_read_b128 v[182:185], v158 offset:2048
	ds_read_b128 v[186:189], v158 offset:3072
	s_add_u32 s74, s72, 0xfff80080
	s_addc_u32 s75, s73, -1
	s_cmp_eq_u32 s96, 28
	s_cselect_b32 s77, s65, s75
	s_cselect_b32 s76, s91, s74
	s_cselect_b32 s75, s63, s95
	s_cselect_b32 s74, s93, s94
	v_lshl_add_u64 v[162:163], s[72:73], 0, v[138:139]
	s_add_i32 m0, s71, 0xc000
	ds_read_b128 v[190:193], v159
	ds_read_b128 v[194:197], v159 offset:1024
	ds_read_b128 v[198:201], v159 offset:2048
	ds_read_b128 v[202:205], v159 offset:3072
	ds_read_b128 v[206:209], v159 offset:4096
	ds_read_b128 v[210:213], v159 offset:5120
	ds_read_b128 v[216:219], v159 offset:6144
	ds_read_b128 v[220:223], v159 offset:7168
	global_load_lds_dwordx4 v[162:163], off
	v_lshl_add_u64 v[162:163], s[72:73], 0, v[140:141]
	s_add_i32 m0, s71, 0xe000
	s_nop 0
	global_load_lds_dwordx4 v[162:163], off
	s_waitcnt vmcnt(8)
	s_waitcnt lgkmcnt(0)
	s_barrier
	s_waitcnt lgkmcnt(0)
	v_mfma_f32_16x16x32_bf16 v[124:127], v[146:149], v[190:193], v[124:127]
	v_mfma_f32_16x16x32_bf16 v[120:123], v[166:169], v[190:193], v[120:123]
	v_mfma_f32_16x16x32_bf16 v[108:111], v[146:149], v[198:201], v[108:111]
	v_mfma_f32_16x16x32_bf16 v[104:107], v[166:169], v[198:201], v[104:107]
	v_mfma_f32_16x16x32_bf16 v[92:95], v[146:149], v[206:209], v[92:95]
	v_mfma_f32_16x16x32_bf16 v[88:91], v[166:169], v[206:209], v[88:91]
	v_mfma_f32_16x16x32_bf16 v[76:79], v[146:149], v[216:219], v[76:79]
	v_mfma_f32_16x16x32_bf16 v[72:75], v[166:169], v[216:219], v[72:75]
	v_mfma_f32_16x16x32_bf16 v[124:127], v[150:153], v[194:197], v[124:127]
	v_mfma_f32_16x16x32_bf16 v[120:123], v[170:173], v[194:197], v[120:123]
	v_mfma_f32_16x16x32_bf16 v[108:111], v[150:153], v[202:205], v[108:111]
	v_mfma_f32_16x16x32_bf16 v[104:107], v[170:173], v[202:205], v[104:107]
	v_mfma_f32_16x16x32_bf16 v[92:95], v[150:153], v[210:213], v[92:95]
	v_mfma_f32_16x16x32_bf16 v[88:91], v[170:173], v[210:213], v[88:91]
	v_mfma_f32_16x16x32_bf16 v[76:79], v[150:153], v[220:223], v[76:79]
	v_mfma_f32_16x16x32_bf16 v[72:75], v[170:173], v[220:223], v[72:75]
	v_mfma_f32_16x16x32_bf16 v[116:119], v[174:177], v[190:193], v[116:119]
	v_mfma_f32_16x16x32_bf16 v[112:115], v[182:185], v[190:193], v[112:115]
	v_mfma_f32_16x16x32_bf16 v[100:103], v[174:177], v[198:201], v[100:103]
	v_mfma_f32_16x16x32_bf16 v[96:99], v[182:185], v[198:201], v[96:99]
	v_mfma_f32_16x16x32_bf16 v[84:87], v[174:177], v[206:209], v[84:87]
	v_mfma_f32_16x16x32_bf16 v[80:83], v[182:185], v[206:209], v[80:83]
	v_mfma_f32_16x16x32_bf16 v[68:71], v[174:177], v[216:219], v[68:71]
	v_mfma_f32_16x16x32_bf16 v[64:67], v[182:185], v[216:219], v[64:67]
	v_mfma_f32_16x16x32_bf16 v[116:119], v[178:181], v[194:197], v[116:119]
	v_mfma_f32_16x16x32_bf16 v[112:115], v[186:189], v[194:197], v[112:115]
	v_mfma_f32_16x16x32_bf16 v[100:103], v[178:181], v[202:205], v[100:103]
	v_mfma_f32_16x16x32_bf16 v[96:99], v[186:189], v[202:205], v[96:99]
	v_mfma_f32_16x16x32_bf16 v[84:87], v[178:181], v[210:213], v[84:87]
	v_mfma_f32_16x16x32_bf16 v[80:83], v[186:189], v[210:213], v[80:83]
	v_mfma_f32_16x16x32_bf16 v[68:71], v[178:181], v[220:223], v[68:71]
	v_mfma_f32_16x16x32_bf16 v[64:67], v[186:189], v[220:223], v[64:67]
	s_barrier
	s_add_i32 s97, s88, s3
	v_lshl_add_u64 v[162:163], s[74:75], 0, v[130:131]
	s_mov_b32 m0, s97
	ds_read_b128 v[190:193], v159 offset:16384
	ds_read_b128 v[194:197], v159 offset:17408
	ds_read_b128 v[198:201], v159 offset:18432
	ds_read_b128 v[202:205], v159 offset:19456
	ds_read_b128 v[206:209], v159 offset:20480
	ds_read_b128 v[210:213], v159 offset:21504
	ds_read_b128 v[216:219], v159 offset:22528
	ds_read_b128 v[220:223], v159 offset:23552
	global_load_lds_dwordx4 v[162:163], off
	s_add_i32 m0, s97, 0x2000
	s_add_u32 vcc_lo, s74, 0x80000
	v_lshl_add_u64 v[224:225], s[74:75], 0, v[134:135]
	s_addc_u32 vcc_hi, s75, 0
	s_add_i32 s97, s89, s3
	global_load_lds_dwordx4 v[224:225], off
	v_lshl_add_u64 v[226:227], vcc, 0, v[130:131]
	s_mov_b32 m0, s97
	v_lshl_add_u64 v[228:229], s[76:77], 0, v[132:133]
	global_load_lds_dwordx4 v[226:227], off
	v_lshl_add_u64 v[226:227], vcc, 0, v[134:135]
	s_add_i32 m0, s97, 0x2000
	s_nop 0
	global_load_lds_dwordx4 v[226:227], off
	v_lshl_add_u64 v[226:227], s[76:77], 0, v[128:129]
	s_mov_b32 m0, s71
	s_nop 0
	global_load_lds_dwordx4 v[226:227], off
	s_mov_b32 m0, s78
	s_nop 0
	global_load_lds_dwordx4 v[228:229], off
	s_waitcnt vmcnt(8)
	s_waitcnt lgkmcnt(0)
	s_barrier
; #define PG8_STAGE(bufoff, gbase, voff) do { _Pragma("unroll") for (int _i = 0; _i < 2; ++_i) \
;         __builtin_amdgcn_global_load_lds((const unsigned*)((const char*)(gbase) + (voff)[_i]), (LAS unsigned*)(lds + (bufoff) + ldsw + _i * 8192), 16, 0, 0); } while (0)
; #define PG8_LDA(dst, b, h) do { _Pragma("unroll") for (int m = 0; m < 4; ++m) _Pragma("unroll") for (int k = 0; k < 2; ++k) dst[m][k] = *(const LAS bf16x8*)(lds + PG8_SA(b, h) + aoff + m * 2048 + k * 1024); } while (0)
; #define PG8_LDB(dst, b, h) do { _Pragma("unroll") for (int n = 0; n < 2; ++n) _Pragma("unroll") for (int k = 0; k < 2; ++k) dst[n][k] = *(const LAS bf16x8*)(lds + PG8_SB(b, h) + boff + n * 2048 + k * 1024); } while (0)
; #define PG8_MMA(ai, bj, At, Bt) do { __builtin_amdgcn_s_setprio(1); _Pragma("unroll") for (int m = 0; m < 4; ++m) _Pragma("unroll") for (int n = 0; n < 2; ++n) _Pragma("unroll") for (int k = 0; k < 2; ++k) \
;         acc[ai][bj][m][n] = __builtin_amdgcn_mfma_f32_16x16x32_bf16(Bt[n][k], At[m][k], acc[ai][bj][m][n], 0, 0, 0); __builtin_amdgcn_s_setprio(0); } while (0)
; #define PG8_WAIT_V(n) asm volatile("s_waitcnt vmcnt(" #n ")" ::: "memory")
; #define PG8_WAIT_L(n) asm volatile("s_waitcnt lgkmcnt(" #n ")" ::: "memory")
; #define PG8_BAR __builtin_amdgcn_s_barrier()
; #define PG8_SCHED __builtin_amdgcn_sched_barrier(0)
; template <class Epi, bool ALIGN_EPI = false, bool SP2 = true>
; __device__ __forceinline__ void gemm_phase(LAS unsigned char* lds, const Gemm g, const StaticOrder& S, const Epi& E) {
;     ...
;             PG8_WAIT_V(8); PG8_WAIT_L(0); PG8_BAR; PG8_MMA(1, 0, At, B0); PG8_MMA(1, 1, At, B1); PG8_BAR; PG8_SCHED;
;             PG8_LDB(B0, 1, 0); PG8_LDB(B1, 1, 1); PG8_SCHED; PG8_LDA(At, 1, 0); PG8_STAGE(PG8_SA(0, 1), a2 + hstep, voffA);
;             PG8_WAIT_V(8); PG8_WAIT_L(0); PG8_BAR; PG8_MMA(0, 0, At, B0); PG8_MMA(0, 1, At, B1); PG8_BAR; PG8_SCHED;
	s_waitcnt lgkmcnt(0)
	v_mfma_f32_16x16x32_bf16 v[60:63], v[146:149], v[190:193], v[60:63]
	v_mfma_f32_16x16x32_bf16 v[56:59], v[166:169], v[190:193], v[56:59]
	v_mfma_f32_16x16x32_bf16 v[44:47], v[146:149], v[198:201], v[44:47]
	v_mfma_f32_16x16x32_bf16 v[40:43], v[166:169], v[198:201], v[40:43]
	v_mfma_f32_16x16x32_bf16 v[28:31], v[146:149], v[206:209], v[28:31]
	v_mfma_f32_16x16x32_bf16 v[24:27], v[166:169], v[206:209], v[24:27]
	v_mfma_f32_16x16x32_bf16 v[12:15], v[146:149], v[216:219], v[12:15]
	v_mfma_f32_16x16x32_bf16 v[8:11], v[166:169], v[216:219], v[8:11]
	v_mfma_f32_16x16x32_bf16 v[60:63], v[150:153], v[194:197], v[60:63]
	v_mfma_f32_16x16x32_bf16 v[56:59], v[170:173], v[194:197], v[56:59]
	v_mfma_f32_16x16x32_bf16 v[44:47], v[150:153], v[202:205], v[44:47]
	v_mfma_f32_16x16x32_bf16 v[40:43], v[170:173], v[202:205], v[40:43]
	v_mfma_f32_16x16x32_bf16 v[28:31], v[150:153], v[210:213], v[28:31]
	v_mfma_f32_16x16x32_bf16 v[24:27], v[170:173], v[210:213], v[24:27]
	v_mfma_f32_16x16x32_bf16 v[12:15], v[150:153], v[220:223], v[12:15]
	v_mfma_f32_16x16x32_bf16 v[8:11], v[170:173], v[220:223], v[8:11]
	v_mfma_f32_16x16x32_bf16 v[52:55], v[174:177], v[190:193], v[52:55]
	v_mfma_f32_16x16x32_bf16 v[48:51], v[182:185], v[190:193], v[48:51]
	v_mfma_f32_16x16x32_bf16 v[36:39], v[174:177], v[198:201], v[36:39]
	v_mfma_f32_16x16x32_bf16 v[32:35], v[182:185], v[198:201], v[32:35]
	v_mfma_f32_16x16x32_bf16 v[20:23], v[174:177], v[206:209], v[20:23]
	v_mfma_f32_16x16x32_bf16 v[16:19], v[182:185], v[206:209], v[16:19]
	v_mfma_f32_16x16x32_bf16 v[4:7], v[174:177], v[216:219], v[4:7]
	v_mfma_f32_16x16x32_bf16 v[0:3], v[182:185], v[216:219], v[0:3]
	v_mfma_f32_16x16x32_bf16 v[52:55], v[178:181], v[194:197], v[52:55]
	v_mfma_f32_16x16x32_bf16 v[48:51], v[186:189], v[194:197], v[48:51]
	v_mfma_f32_16x16x32_bf16 v[36:39], v[178:181], v[202:205], v[36:39]
	v_mfma_f32_16x16x32_bf16 v[32:35], v[186:189], v[202:205], v[32:35]
	v_mfma_f32_16x16x32_bf16 v[20:23], v[178:181], v[210:213], v[20:23]
	v_mfma_f32_16x16x32_bf16 v[16:19], v[186:189], v[210:213], v[16:19]
	v_mfma_f32_16x16x32_bf16 v[4:7], v[178:181], v[220:223], v[4:7]
	v_mfma_f32_16x16x32_bf16 v[0:3], v[186:189], v[220:223], v[0:3]
	s_barrier
	s_add_i32 s97, 0, 0x18000
	v_add_u32_e32 v136, s97, v155
	s_add_i32 vcc_lo, 0, 0x1c000
	ds_read_b128 v[146:149], v136
	ds_read_b128 v[150:153], v136 offset:1024
	ds_read_b128 v[166:169], v136 offset:2048
	ds_read_b128 v[170:173], v136 offset:3072
	v_add_u32_e32 v136, vcc_lo, v155
	ds_read_b128 v[174:177], v136
	ds_read_b128 v[178:181], v136 offset:1024
	ds_read_b128 v[182:185], v136 offset:2048
	ds_read_b128 v[186:189], v136 offset:3072
	s_add_u32 s76, s76, 0x80000
	s_addc_u32 s77, s77, 0
	s_mov_b32 m0, s79
	v_lshl_add_u64 v[230:231], s[76:77], 0, v[128:129]
	ds_read_b128 v[190:193], v159 offset:32768
	ds_read_b128 v[194:197], v159 offset:33792
	ds_read_b128 v[198:201], v159 offset:34816
	ds_read_b128 v[202:205], v159 offset:35840
	ds_read_b128 v[206:209], v159 offset:36864
	ds_read_b128 v[210:213], v159 offset:37888
	ds_read_b128 v[216:219], v159 offset:38912
	ds_read_b128 v[220:223], v159 offset:39936
	global_load_lds_dwordx4 v[230:231], off
	v_lshl_add_u64 v[230:231], s[76:77], 0, v[132:133]
	s_mov_b32 m0, s80
	s_nop 0
	global_load_lds_dwordx4 v[230:231], off
	s_waitcnt vmcnt(8)
	s_waitcnt lgkmcnt(0)
	s_barrier
	s_waitcnt lgkmcnt(0)
	v_mfma_f32_16x16x32_bf16 v[124:127], v[146:149], v[190:193], v[124:127]
	v_mfma_f32_16x16x32_bf16 v[120:123], v[166:169], v[190:193], v[120:123]
	v_mfma_f32_16x16x32_bf16 v[108:111], v[146:149], v[198:201], v[108:111]
	v_mfma_f32_16x16x32_bf16 v[104:107], v[166:169], v[198:201], v[104:107]
	v_mfma_f32_16x16x32_bf16 v[92:95], v[146:149], v[206:209], v[92:95]
	v_mfma_f32_16x16x32_bf16 v[88:91], v[166:169], v[206:209], v[88:91]
	v_mfma_f32_16x16x32_bf16 v[76:79], v[146:149], v[216:219], v[76:79]
	v_mfma_f32_16x16x32_bf16 v[72:75], v[166:169], v[216:219], v[72:75]
	v_mfma_f32_16x16x32_bf16 v[124:127], v[150:153], v[194:197], v[124:127]
	v_mfma_f32_16x16x32_bf16 v[120:123], v[170:173], v[194:197], v[120:123]
	v_mfma_f32_16x16x32_bf16 v[108:111], v[150:153], v[202:205], v[108:111]
	v_mfma_f32_16x16x32_bf16 v[104:107], v[170:173], v[202:205], v[104:107]
	v_mfma_f32_16x16x32_bf16 v[92:95], v[150:153], v[210:213], v[92:95]
	v_mfma_f32_16x16x32_bf16 v[88:91], v[170:173], v[210:213], v[88:91]
	v_mfma_f32_16x16x32_bf16 v[76:79], v[150:153], v[220:223], v[76:79]
	v_mfma_f32_16x16x32_bf16 v[72:75], v[170:173], v[220:223], v[72:75]
	v_mfma_f32_16x16x32_bf16 v[116:119], v[174:177], v[190:193], v[116:119]
	v_mfma_f32_16x16x32_bf16 v[112:115], v[182:185], v[190:193], v[112:115]
	v_mfma_f32_16x16x32_bf16 v[100:103], v[174:177], v[198:201], v[100:103]
	v_mfma_f32_16x16x32_bf16 v[96:99], v[182:185], v[198:201], v[96:99]
	v_mfma_f32_16x16x32_bf16 v[84:87], v[174:177], v[206:209], v[84:87]
	v_mfma_f32_16x16x32_bf16 v[80:83], v[182:185], v[206:209], v[80:83]
	v_mfma_f32_16x16x32_bf16 v[68:71], v[174:177], v[216:219], v[68:71]
	v_mfma_f32_16x16x32_bf16 v[64:67], v[182:185], v[216:219], v[64:67]
	v_mfma_f32_16x16x32_bf16 v[116:119], v[178:181], v[194:197], v[116:119]
	v_mfma_f32_16x16x32_bf16 v[112:115], v[186:189], v[194:197], v[112:115]
	v_mfma_f32_16x16x32_bf16 v[100:103], v[178:181], v[202:205], v[100:103]
	v_mfma_f32_16x16x32_bf16 v[96:99], v[186:189], v[202:205], v[96:99]
	v_mfma_f32_16x16x32_bf16 v[84:87], v[178:181], v[210:213], v[84:87]
	v_mfma_f32_16x16x32_bf16 v[80:83], v[186:189], v[210:213], v[80:83]
	v_mfma_f32_16x16x32_bf16 v[68:71], v[178:181], v[220:223], v[68:71]
	v_mfma_f32_16x16x32_bf16 v[64:67], v[186:189], v[220:223], v[64:67]
	s_barrier
; #define PG8_STAGE(bufoff, gbase, voff) do { _Pragma("unroll") for (int _i = 0; _i < 2; ++_i) \
;         __builtin_amdgcn_global_load_lds((const unsigned*)((const char*)(gbase) + (voff)[_i]), (LAS unsigned*)(lds + (bufoff) + ldsw + _i * 8192), 16, 0, 0); } while (0)
; #define PG8_LDA(dst, b, h) do { _Pragma("unroll") for (int m = 0; m < 4; ++m) _Pragma("unroll") for (int k = 0; k < 2; ++k) dst[m][k] = *(const LAS bf16x8*)(lds + PG8_SA(b, h) + aoff + m * 2048 + k * 1024); } while (0)
; #define PG8_MMA(ai, bj, At, Bt) do { __builtin_amdgcn_s_setprio(1); _Pragma("unroll") for (int m = 0; m < 4; ++m) _Pragma("unroll") for (int n = 0; n < 2; ++n) _Pragma("unroll") for (int k = 0; k < 2; ++k) \
;         acc[ai][bj][m][n] = __builtin_amdgcn_mfma_f32_16x16x32_bf16(Bt[n][k], At[m][k], acc[ai][bj][m][n], 0, 0, 0); __builtin_amdgcn_s_setprio(0); } while (0)
; #define PG8_WAIT_V(n) asm volatile("s_waitcnt vmcnt(" #n ")" ::: "memory")
; #define PG8_WAIT_L(n) asm volatile("s_waitcnt lgkmcnt(" #n ")" ::: "memory")
; #define PG8_BAR __builtin_amdgcn_s_barrier()
; #define PG8_SCHED __builtin_amdgcn_sched_barrier(0)
; template <class Epi, bool ALIGN_EPI = false, bool SP2 = true>
; __device__ __forceinline__ void gemm_phase(LAS unsigned char* lds, const Gemm g, const StaticOrder& S, const Epi& E) {
;     ...
;         for (int t = 0; t < nt; t += 2) {
;             const bool last = (t == nt - 2);
;             const char* a1 = cA + (size_t)(t + 1) * kstep;
;             const char* a2 = last ? nA : cA + (size_t)(t + 2) * kstep; const char* b2 = last ? nB : cB + (size_t)(t + 2) * kstep;
;     ...
;             PG8_LDA(At, 1, 1); PG8_STAGE(PG8_SB(1, 0), b3, voffB); PG8_STAGE(PG8_SB(1, 1), b3 + hstep, voffB); PG8_STAGE(PG8_SA(1, 0), a3, voffA);
;             PG8_WAIT_V(8); PG8_WAIT_L(0); PG8_BAR; PG8_MMA(1, 0, At, B0); PG8_MMA(1, 1, At, B1); PG8_BAR; PG8_SCHED;
	s_add_i32 s76, s97, s3
	v_lshl_add_u64 v[162:163], v[162:163], 0, s[36:37]
	s_mov_b32 m0, s76
	ds_read_b128 v[190:193], v159 offset:49152
	ds_read_b128 v[194:197], v159 offset:50176
	ds_read_b128 v[198:201], v159 offset:51200
	ds_read_b128 v[202:205], v159 offset:52224
	ds_read_b128 v[206:209], v159 offset:53248
	ds_read_b128 v[210:213], v159 offset:54272
	ds_read_b128 v[216:219], v159 offset:55296
	ds_read_b128 v[220:223], v159 offset:56320
	global_load_lds_dwordx4 v[162:163], off
	s_add_i32 m0, s76, 0x2000
	s_add_u32 s74, s74, 0x80080
	v_lshl_add_u64 v[162:163], v[224:225], 0, s[36:37]
	s_addc_u32 s75, s75, 0
	s_add_i32 s76, vcc_lo, s3
	global_load_lds_dwordx4 v[162:163], off
	v_lshl_add_u64 v[162:163], s[74:75], 0, v[130:131]
	s_mov_b32 m0, s76
	s_nop 0
	global_load_lds_dwordx4 v[162:163], off
	v_lshl_add_u64 v[162:163], s[74:75], 0, v[134:135]
	s_add_i32 m0, s76, 0x2000
	s_nop 0
	global_load_lds_dwordx4 v[162:163], off
	v_lshl_add_u64 v[162:163], v[226:227], 0, s[36:37]
	s_mov_b32 m0, s82
	s_nop 0
	global_load_lds_dwordx4 v[162:163], off
	v_lshl_add_u64 v[162:163], v[228:229], 0, s[36:37]
	s_mov_b32 m0, s83
	s_nop 0
	global_load_lds_dwordx4 v[162:163], off
	s_waitcnt vmcnt(8)
	s_waitcnt lgkmcnt(0)
	s_barrier
	s_waitcnt lgkmcnt(0)
	v_mfma_f32_16x16x32_bf16 v[60:63], v[146:149], v[190:193], v[60:63]
	v_mfma_f32_16x16x32_bf16 v[56:59], v[166:169], v[190:193], v[56:59]
	v_mfma_f32_16x16x32_bf16 v[44:47], v[146:149], v[198:201], v[44:47]
	v_mfma_f32_16x16x32_bf16 v[40:43], v[166:169], v[198:201], v[40:43]
	v_mfma_f32_16x16x32_bf16 v[28:31], v[146:149], v[206:209], v[28:31]
	v_mfma_f32_16x16x32_bf16 v[24:27], v[166:169], v[206:209], v[24:27]
	v_mfma_f32_16x16x32_bf16 v[12:15], v[146:149], v[216:219], v[12:15]
	v_mfma_f32_16x16x32_bf16 v[8:11], v[166:169], v[216:219], v[8:11]
	v_mfma_f32_16x16x32_bf16 v[60:63], v[150:153], v[194:197], v[60:63]
	v_mfma_f32_16x16x32_bf16 v[56:59], v[170:173], v[194:197], v[56:59]
	v_mfma_f32_16x16x32_bf16 v[44:47], v[150:153], v[202:205], v[44:47]
	v_mfma_f32_16x16x32_bf16 v[40:43], v[170:173], v[202:205], v[40:43]
	v_mfma_f32_16x16x32_bf16 v[28:31], v[150:153], v[210:213], v[28:31]
	v_mfma_f32_16x16x32_bf16 v[24:27], v[170:173], v[210:213], v[24:27]
	v_mfma_f32_16x16x32_bf16 v[12:15], v[150:153], v[220:223], v[12:15]
	v_mfma_f32_16x16x32_bf16 v[8:11], v[170:173], v[220:223], v[8:11]
	v_mfma_f32_16x16x32_bf16 v[52:55], v[174:177], v[190:193], v[52:55]
	v_mfma_f32_16x16x32_bf16 v[48:51], v[182:185], v[190:193], v[48:51]
	v_mfma_f32_16x16x32_bf16 v[36:39], v[174:177], v[198:201], v[36:39]
	v_mfma_f32_16x16x32_bf16 v[32:35], v[182:185], v[198:201], v[32:35]
	v_mfma_f32_16x16x32_bf16 v[20:23], v[174:177], v[206:209], v[20:23]
	v_mfma_f32_16x16x32_bf16 v[16:19], v[182:185], v[206:209], v[16:19]
	v_mfma_f32_16x16x32_bf16 v[4:7], v[174:177], v[216:219], v[4:7]
	v_mfma_f32_16x16x32_bf16 v[0:3], v[182:185], v[216:219], v[0:3]
	v_mfma_f32_16x16x32_bf16 v[52:55], v[178:181], v[194:197], v[52:55]
	v_mfma_f32_16x16x32_bf16 v[48:51], v[186:189], v[194:197], v[48:51]
	v_mfma_f32_16x16x32_bf16 v[36:39], v[178:181], v[202:205], v[36:39]
	v_mfma_f32_16x16x32_bf16 v[32:35], v[186:189], v[202:205], v[32:35]
	v_mfma_f32_16x16x32_bf16 v[20:23], v[178:181], v[210:213], v[20:23]
	v_mfma_f32_16x16x32_bf16 v[16:19], v[186:189], v[210:213], v[16:19]
	v_mfma_f32_16x16x32_bf16 v[4:7], v[178:181], v[220:223], v[4:7]
	v_mfma_f32_16x16x32_bf16 v[0:3], v[186:189], v[220:223], v[0:3]
	s_add_i32 s96, s96, 2
	s_add_u32 s72, s72, 0x100
	s_addc_u32 s73, s73, 0
	s_add_u32 s94, s94, 0x100
	s_addc_u32 s95, s95, 0
	s_cmp_gt_u32 s96, 29
	s_barrier
	s_cbranch_scc0 .LBB0_155
	s_and_b64 vcc, exec, s[60:61]
	s_cbranch_vccz .LBB0_158
	s_barrier

; #define PG8_STAGE(bufoff, gbase, voff) do { _Pragma("unroll") for (int _i = 0; _i < 2; ++_i) \
;         __builtin_amdgcn_global_load_lds((const unsigned*)((const char*)(gbase) + (voff)[_i]), (LAS unsigned*)(lds + (bufoff) + ldsw + _i * 8192), 16, 0, 0); } while (0)
; #define PG8_LDA(dst, b, h) do { _Pragma("unroll") for (int m = 0; m < 4; ++m) _Pragma("unroll") for (int k = 0; k < 2; ++k) dst[m][k] = *(const LAS bf16x8*)(lds + PG8_SA(b, h) + aoff + m * 2048 + k * 1024); } while (0)
; #define PG8_LDB(dst, b, h) do { _Pragma("unroll") for (int n = 0; n < 2; ++n) _Pragma("unroll") for (int k = 0; k < 2; ++k) dst[n][k] = *(const LAS bf16x8*)(lds + PG8_SB(b, h) + boff + n * 2048 + k * 1024); } while (0)
; #define PG8_MMA(ai, bj, At, Bt) do { __builtin_amdgcn_s_setprio(1); _Pragma("unroll") for (int m = 0; m < 4; ++m) _Pragma("unroll") for (int n = 0; n < 2; ++n) _Pragma("unroll") for (int k = 0; k < 2; ++k) \
;         acc[ai][bj][m][n] = __builtin_amdgcn_mfma_f32_16x16x32_bf16(Bt[n][k], At[m][k], acc[ai][bj][m][n], 0, 0, 0); __builtin_amdgcn_s_setprio(0); } while (0)
; #define PG8_WAIT_V(n) asm volatile("s_waitcnt vmcnt(" #n ")" ::: "memory")
; #define PG8_WAIT_L(n) asm volatile("s_waitcnt lgkmcnt(" #n ")" ::: "memory")
; #define PG8_BAR __builtin_amdgcn_s_barrier()
; #define PG8_SCHED __builtin_amdgcn_sched_barrier(0)
; template <class Epi, bool ALIGN_EPI = false, bool SP2 = true>
; __device__ __forceinline__ void gemm_phase(LAS unsigned char* lds, const Gemm g, const StaticOrder& S, const Epi& E) {
;     ...
;             PG8_LDB(B0, 0, 0); PG8_LDB(B1, 0, 1); PG8_SCHED; PG8_LDA(At, 0, 0); PG8_STAGE(PG8_SA(1, 1), a1 + hstep, voffA);
;             PG8_WAIT_V(8); PG8_WAIT_L(0); PG8_BAR; PG8_MMA(0, 0, At, B0); PG8_MMA(0, 1, At, B1); PG8_BAR; PG8_SCHED;
;             PG8_LDA(At, 0, 1); PG8_STAGE(PG8_SB(0, 0), b2, voffB); PG8_STAGE(PG8_SB(0, 1), b2 + hstep, voffB); PG8_STAGE(PG8_SA(0, 0), a2, voffA);
;             PG8_WAIT_V(8); PG8_WAIT_L(0); PG8_BAR; PG8_MMA(1, 0, At, B0); PG8_MMA(1, 1, At, B1); PG8_BAR; PG8_SCHED;
.LBB0_325:
	v_add_u32_e32 v161, s76, v150
	s_waitcnt lgkmcnt(0)
	ds_read_b128 v[152:155], v161
	ds_read_b128 v[156:159], v161 offset:1024
	ds_read_b128 v[166:169], v161 offset:2048
	ds_read_b128 v[170:173], v161 offset:3072
	v_add_u32_e32 v161, s77, v150
	s_add_u32 s62, s0, s60
	ds_read_b128 v[174:177], v161
	ds_read_b128 v[178:181], v161 offset:1024
	ds_read_b128 v[182:185], v161 offset:2048
	ds_read_b128 v[186:189], v161 offset:3072
	s_addc_u32 s63, s1, s61
	s_add_u32 s62, s62, 0x100
	s_addc_u32 s63, s63, 0
	s_add_u32 s84, s79, s60
	s_addc_u32 s85, s80, s61
	s_cmpk_eq_i32 s60, 0xf00
	s_cselect_b32 s65, s29, s63
	s_cselect_b32 s64, s81, s62
	s_cselect_b32 s63, s27, s85
	s_cselect_b32 s62, s82, s84
	v_lshl_add_u64 v[162:163], v[144:145], 0, s[60:61]
	s_add_i32 m0, s68, 0xc000
	ds_read_b128 v[190:193], v151
	ds_read_b128 v[194:197], v151 offset:1024
	ds_read_b128 v[198:201], v151 offset:2048
	ds_read_b128 v[202:205], v151 offset:3072
	ds_read_b128 v[206:209], v151 offset:4096
	ds_read_b128 v[210:213], v151 offset:5120
	ds_read_b128 v[216:219], v151 offset:6144
	ds_read_b128 v[220:223], v151 offset:7168
	global_load_lds_dwordx4 v[162:163], off
	v_lshl_add_u64 v[162:163], v[146:147], 0, s[60:61]
	s_add_i32 m0, s68, 0xe000
	s_nop 0
	global_load_lds_dwordx4 v[162:163], off
	s_waitcnt vmcnt(8)
	s_waitcnt lgkmcnt(0)
	s_barrier
	s_waitcnt lgkmcnt(0)
	v_mfma_f32_16x16x32_bf16 v[124:127], v[152:155], v[190:193], v[124:127]
	v_mfma_f32_16x16x32_bf16 v[120:123], v[166:169], v[190:193], v[120:123]
	v_mfma_f32_16x16x32_bf16 v[108:111], v[152:155], v[198:201], v[108:111]
	v_mfma_f32_16x16x32_bf16 v[104:107], v[166:169], v[198:201], v[104:107]
	v_mfma_f32_16x16x32_bf16 v[92:95], v[152:155], v[206:209], v[92:95]
	v_mfma_f32_16x16x32_bf16 v[88:91], v[166:169], v[206:209], v[88:91]
	v_mfma_f32_16x16x32_bf16 v[76:79], v[152:155], v[216:219], v[76:79]
	v_mfma_f32_16x16x32_bf16 v[72:75], v[166:169], v[216:219], v[72:75]
	v_mfma_f32_16x16x32_bf16 v[124:127], v[156:159], v[194:197], v[124:127]
	v_mfma_f32_16x16x32_bf16 v[120:123], v[170:173], v[194:197], v[120:123]
	v_mfma_f32_16x16x32_bf16 v[108:111], v[156:159], v[202:205], v[108:111]
	v_mfma_f32_16x16x32_bf16 v[104:107], v[170:173], v[202:205], v[104:107]
	v_mfma_f32_16x16x32_bf16 v[92:95], v[156:159], v[210:213], v[92:95]
	v_mfma_f32_16x16x32_bf16 v[88:91], v[170:173], v[210:213], v[88:91]
	v_mfma_f32_16x16x32_bf16 v[76:79], v[156:159], v[220:223], v[76:79]
	v_mfma_f32_16x16x32_bf16 v[72:75], v[170:173], v[220:223], v[72:75]
	v_mfma_f32_16x16x32_bf16 v[116:119], v[174:177], v[190:193], v[116:119]
	v_mfma_f32_16x16x32_bf16 v[112:115], v[182:185], v[190:193], v[112:115]
	v_mfma_f32_16x16x32_bf16 v[100:103], v[174:177], v[198:201], v[100:103]
	v_mfma_f32_16x16x32_bf16 v[96:99], v[182:185], v[198:201], v[96:99]
	v_mfma_f32_16x16x32_bf16 v[84:87], v[174:177], v[206:209], v[84:87]
	v_mfma_f32_16x16x32_bf16 v[80:83], v[182:185], v[206:209], v[80:83]
	v_mfma_f32_16x16x32_bf16 v[68:71], v[174:177], v[216:219], v[68:71]
	v_mfma_f32_16x16x32_bf16 v[64:67], v[182:185], v[216:219], v[64:67]
	v_mfma_f32_16x16x32_bf16 v[116:119], v[178:181], v[194:197], v[116:119]
	v_mfma_f32_16x16x32_bf16 v[112:115], v[186:189], v[194:197], v[112:115]
	v_mfma_f32_16x16x32_bf16 v[100:103], v[178:181], v[202:205], v[100:103]
	v_mfma_f32_16x16x32_bf16 v[96:99], v[186:189], v[202:205], v[96:99]
	v_mfma_f32_16x16x32_bf16 v[84:87], v[178:181], v[210:213], v[84:87]
	v_mfma_f32_16x16x32_bf16 v[80:83], v[186:189], v[210:213], v[80:83]
	v_mfma_f32_16x16x32_bf16 v[68:71], v[178:181], v[220:223], v[68:71]
	v_mfma_f32_16x16x32_bf16 v[64:67], v[186:189], v[220:223], v[64:67]
	s_barrier
	s_add_i32 s84, s76, s67
	v_lshl_add_u64 v[162:163], s[62:63], 0, v[130:131]
	s_mov_b32 m0, s84
	ds_read_b128 v[190:193], v151 offset:16384
	ds_read_b128 v[194:197], v151 offset:17408
	ds_read_b128 v[198:201], v151 offset:18432
	ds_read_b128 v[202:205], v151 offset:19456
	ds_read_b128 v[206:209], v151 offset:20480
	ds_read_b128 v[210:213], v151 offset:21504
	ds_read_b128 v[216:219], v151 offset:22528
	ds_read_b128 v[220:223], v151 offset:23552
	global_load_lds_dwordx4 v[162:163], off
	s_add_i32 m0, s84, 0x2000
	s_add_u32 s84, s62, 0x80000
	v_lshl_add_u64 v[224:225], s[62:63], 0, v[134:135]
	s_addc_u32 s85, s63, 0
	s_add_i32 s86, s77, s67
	global_load_lds_dwordx4 v[224:225], off
	v_lshl_add_u64 v[226:227], s[84:85], 0, v[130:131]
	s_mov_b32 m0, s86
	v_lshl_add_u64 v[228:229], s[64:65], 0, v[132:133]
	global_load_lds_dwordx4 v[226:227], off
	v_lshl_add_u64 v[226:227], s[84:85], 0, v[134:135]
	s_add_i32 m0, s86, 0x2000
	s_nop 0
	global_load_lds_dwordx4 v[226:227], off
	v_lshl_add_u64 v[226:227], s[64:65], 0, v[128:129]
	s_mov_b32 m0, s68
	s_nop 0
	global_load_lds_dwordx4 v[226:227], off
	s_mov_b32 m0, s69
	s_nop 0
	global_load_lds_dwordx4 v[228:229], off
	s_waitcnt vmcnt(8)
	s_waitcnt lgkmcnt(0)
	s_barrier
; #define PG8_STAGE(bufoff, gbase, voff) do { _Pragma("unroll") for (int _i = 0; _i < 2; ++_i) \
;         __builtin_amdgcn_global_load_lds((const unsigned*)((const char*)(gbase) + (voff)[_i]), (LAS unsigned*)(lds + (bufoff) + ldsw + _i * 8192), 16, 0, 0); } while (0)
; #define PG8_LDA(dst, b, h) do { _Pragma("unroll") for (int m = 0; m < 4; ++m) _Pragma("unroll") for (int k = 0; k < 2; ++k) dst[m][k] = *(const LAS bf16x8*)(lds + PG8_SA(b, h) + aoff + m * 2048 + k * 1024); } while (0)
; #define PG8_LDB(dst, b, h) do { _Pragma("unroll") for (int n = 0; n < 2; ++n) _Pragma("unroll") for (int k = 0; k < 2; ++k) dst[n][k] = *(const LAS bf16x8*)(lds + PG8_SB(b, h) + boff + n * 2048 + k * 1024); } while (0)
; #define PG8_MMA(ai, bj, At, Bt) do { __builtin_amdgcn_s_setprio(1); _Pragma("unroll") for (int m = 0; m < 4; ++m) _Pragma("unroll") for (int n = 0; n < 2; ++n) _Pragma("unroll") for (int k = 0; k < 2; ++k) \
;         acc[ai][bj][m][n] = __builtin_amdgcn_mfma_f32_16x16x32_bf16(Bt[n][k], At[m][k], acc[ai][bj][m][n], 0, 0, 0); __builtin_amdgcn_s_setprio(0); } while (0)
; #define PG8_WAIT_V(n) asm volatile("s_waitcnt vmcnt(" #n ")" ::: "memory")
; #define PG8_WAIT_L(n) asm volatile("s_waitcnt lgkmcnt(" #n ")" ::: "memory")
; #define PG8_BAR __builtin_amdgcn_s_barrier()
; #define PG8_SCHED __builtin_amdgcn_sched_barrier(0)
; template <class Epi, bool ALIGN_EPI = false, bool SP2 = true>
; __device__ __forceinline__ void gemm_phase(LAS unsigned char* lds, const Gemm g, const StaticOrder& S, const Epi& E) {
;     ...
;             PG8_WAIT_V(8); PG8_WAIT_L(0); PG8_BAR; PG8_MMA(1, 0, At, B0); PG8_MMA(1, 1, At, B1); PG8_BAR; PG8_SCHED;
;             PG8_LDB(B0, 1, 0); PG8_LDB(B1, 1, 1); PG8_SCHED; PG8_LDA(At, 1, 0); PG8_STAGE(PG8_SA(0, 1), a2 + hstep, voffA);
;             PG8_WAIT_V(8); PG8_WAIT_L(0); PG8_BAR; PG8_MMA(0, 0, At, B0); PG8_MMA(0, 1, At, B1); PG8_BAR; PG8_SCHED;
	s_waitcnt lgkmcnt(0)
	v_mfma_f32_16x16x32_bf16 v[60:63], v[152:155], v[190:193], v[60:63]
	v_mfma_f32_16x16x32_bf16 v[56:59], v[166:169], v[190:193], v[56:59]
	v_mfma_f32_16x16x32_bf16 v[44:47], v[152:155], v[198:201], v[44:47]
	v_mfma_f32_16x16x32_bf16 v[40:43], v[166:169], v[198:201], v[40:43]
	v_mfma_f32_16x16x32_bf16 v[28:31], v[152:155], v[206:209], v[28:31]
	v_mfma_f32_16x16x32_bf16 v[24:27], v[166:169], v[206:209], v[24:27]
	v_mfma_f32_16x16x32_bf16 v[12:15], v[152:155], v[216:219], v[12:15]
	v_mfma_f32_16x16x32_bf16 v[8:11], v[166:169], v[216:219], v[8:11]
	v_mfma_f32_16x16x32_bf16 v[60:63], v[156:159], v[194:197], v[60:63]
	v_mfma_f32_16x16x32_bf16 v[56:59], v[170:173], v[194:197], v[56:59]
	v_mfma_f32_16x16x32_bf16 v[44:47], v[156:159], v[202:205], v[44:47]
	v_mfma_f32_16x16x32_bf16 v[40:43], v[170:173], v[202:205], v[40:43]
	v_mfma_f32_16x16x32_bf16 v[28:31], v[156:159], v[210:213], v[28:31]
	v_mfma_f32_16x16x32_bf16 v[24:27], v[170:173], v[210:213], v[24:27]
	v_mfma_f32_16x16x32_bf16 v[12:15], v[156:159], v[220:223], v[12:15]
	v_mfma_f32_16x16x32_bf16 v[8:11], v[170:173], v[220:223], v[8:11]
	v_mfma_f32_16x16x32_bf16 v[52:55], v[174:177], v[190:193], v[52:55]
	v_mfma_f32_16x16x32_bf16 v[48:51], v[182:185], v[190:193], v[48:51]
	v_mfma_f32_16x16x32_bf16 v[36:39], v[174:177], v[198:201], v[36:39]
	v_mfma_f32_16x16x32_bf16 v[32:35], v[182:185], v[198:201], v[32:35]
	v_mfma_f32_16x16x32_bf16 v[20:23], v[174:177], v[206:209], v[20:23]
	v_mfma_f32_16x16x32_bf16 v[16:19], v[182:185], v[206:209], v[16:19]
	v_mfma_f32_16x16x32_bf16 v[4:7], v[174:177], v[216:219], v[4:7]
	v_mfma_f32_16x16x32_bf16 v[0:3], v[182:185], v[216:219], v[0:3]
	v_mfma_f32_16x16x32_bf16 v[52:55], v[178:181], v[194:197], v[52:55]
	v_mfma_f32_16x16x32_bf16 v[48:51], v[186:189], v[194:197], v[48:51]
	v_mfma_f32_16x16x32_bf16 v[36:39], v[178:181], v[202:205], v[36:39]
	v_mfma_f32_16x16x32_bf16 v[32:35], v[186:189], v[202:205], v[32:35]
	v_mfma_f32_16x16x32_bf16 v[20:23], v[178:181], v[210:213], v[20:23]
	v_mfma_f32_16x16x32_bf16 v[16:19], v[186:189], v[210:213], v[16:19]
	v_mfma_f32_16x16x32_bf16 v[4:7], v[178:181], v[220:223], v[4:7]
	v_mfma_f32_16x16x32_bf16 v[0:3], v[186:189], v[220:223], v[0:3]
	s_barrier
	s_add_i32 s84, 0, 0x18000
	v_add_u32_e32 v161, s84, v150
	s_add_i32 s85, 0, 0x1c000
	ds_read_b128 v[152:155], v161
	ds_read_b128 v[156:159], v161 offset:1024
	ds_read_b128 v[166:169], v161 offset:2048
	ds_read_b128 v[170:173], v161 offset:3072
	v_add_u32_e32 v161, s85, v150
	ds_read_b128 v[174:177], v161
	ds_read_b128 v[178:181], v161 offset:1024
	ds_read_b128 v[182:185], v161 offset:2048
	ds_read_b128 v[186:189], v161 offset:3072
	s_add_u32 s64, s64, 0x80000
	s_addc_u32 s65, s65, 0
	s_mov_b32 m0, s70
	v_lshl_add_u64 v[230:231], s[64:65], 0, v[128:129]
	ds_read_b128 v[190:193], v151 offset:32768
	ds_read_b128 v[194:197], v151 offset:33792
	ds_read_b128 v[198:201], v151 offset:34816
	ds_read_b128 v[202:205], v151 offset:35840
	ds_read_b128 v[206:209], v151 offset:36864
	ds_read_b128 v[210:213], v151 offset:37888
	ds_read_b128 v[216:219], v151 offset:38912
	ds_read_b128 v[220:223], v151 offset:39936
	global_load_lds_dwordx4 v[230:231], off
	v_lshl_add_u64 v[230:231], s[64:65], 0, v[132:133]
	s_mov_b32 m0, s71
	s_nop 0
	global_load_lds_dwordx4 v[230:231], off
	s_waitcnt vmcnt(8)
	s_waitcnt lgkmcnt(0)
	s_barrier
	s_waitcnt lgkmcnt(0)
	v_mfma_f32_16x16x32_bf16 v[124:127], v[152:155], v[190:193], v[124:127]
	v_mfma_f32_16x16x32_bf16 v[120:123], v[166:169], v[190:193], v[120:123]
	v_mfma_f32_16x16x32_bf16 v[108:111], v[152:155], v[198:201], v[108:111]
	v_mfma_f32_16x16x32_bf16 v[104:107], v[166:169], v[198:201], v[104:107]
	v_mfma_f32_16x16x32_bf16 v[92:95], v[152:155], v[206:209], v[92:95]
	v_mfma_f32_16x16x32_bf16 v[88:91], v[166:169], v[206:209], v[88:91]
	v_mfma_f32_16x16x32_bf16 v[76:79], v[152:155], v[216:219], v[76:79]
	v_mfma_f32_16x16x32_bf16 v[72:75], v[166:169], v[216:219], v[72:75]
	v_mfma_f32_16x16x32_bf16 v[124:127], v[156:159], v[194:197], v[124:127]
	v_mfma_f32_16x16x32_bf16 v[120:123], v[170:173], v[194:197], v[120:123]
	v_mfma_f32_16x16x32_bf16 v[108:111], v[156:159], v[202:205], v[108:111]
	v_mfma_f32_16x16x32_bf16 v[104:107], v[170:173], v[202:205], v[104:107]
	v_mfma_f32_16x16x32_bf16 v[92:95], v[156:159], v[210:213], v[92:95]
	v_mfma_f32_16x16x32_bf16 v[88:91], v[170:173], v[210:213], v[88:91]
	v_mfma_f32_16x16x32_bf16 v[76:79], v[156:159], v[220:223], v[76:79]
	v_mfma_f32_16x16x32_bf16 v[72:75], v[170:173], v[220:223], v[72:75]
	v_mfma_f32_16x16x32_bf16 v[116:119], v[174:177], v[190:193], v[116:119]
	v_mfma_f32_16x16x32_bf16 v[112:115], v[182:185], v[190:193], v[112:115]
	v_mfma_f32_16x16x32_bf16 v[100:103], v[174:177], v[198:201], v[100:103]
	v_mfma_f32_16x16x32_bf16 v[96:99], v[182:185], v[198:201], v[96:99]
	v_mfma_f32_16x16x32_bf16 v[84:87], v[174:177], v[206:209], v[84:87]
	v_mfma_f32_16x16x32_bf16 v[80:83], v[182:185], v[206:209], v[80:83]
	v_mfma_f32_16x16x32_bf16 v[68:71], v[174:177], v[216:219], v[68:71]
	v_mfma_f32_16x16x32_bf16 v[64:67], v[182:185], v[216:219], v[64:67]
	v_mfma_f32_16x16x32_bf16 v[116:119], v[178:181], v[194:197], v[116:119]
	v_mfma_f32_16x16x32_bf16 v[112:115], v[186:189], v[194:197], v[112:115]
	v_mfma_f32_16x16x32_bf16 v[100:103], v[178:181], v[202:205], v[100:103]
	v_mfma_f32_16x16x32_bf16 v[96:99], v[186:189], v[202:205], v[96:99]
	v_mfma_f32_16x16x32_bf16 v[84:87], v[178:181], v[210:213], v[84:87]
	v_mfma_f32_16x16x32_bf16 v[80:83], v[186:189], v[210:213], v[80:83]
	v_mfma_f32_16x16x32_bf16 v[68:71], v[178:181], v[220:223], v[68:71]
	v_mfma_f32_16x16x32_bf16 v[64:67], v[186:189], v[220:223], v[64:67]
	s_barrier
; #define PG8_STAGE(bufoff, gbase, voff) do { _Pragma("unroll") for (int _i = 0; _i < 2; ++_i) \
;         __builtin_amdgcn_global_load_lds((const unsigned*)((const char*)(gbase) + (voff)[_i]), (LAS unsigned*)(lds + (bufoff) + ldsw + _i * 8192), 16, 0, 0); } while (0)
; #define PG8_LDA(dst, b, h) do { _Pragma("unroll") for (int m = 0; m < 4; ++m) _Pragma("unroll") for (int k = 0; k < 2; ++k) dst[m][k] = *(const LAS bf16x8*)(lds + PG8_SA(b, h) + aoff + m * 2048 + k * 1024); } while (0)
; #define PG8_MMA(ai, bj, At, Bt) do { __builtin_amdgcn_s_setprio(1); _Pragma("unroll") for (int m = 0; m < 4; ++m) _Pragma("unroll") for (int n = 0; n < 2; ++n) _Pragma("unroll") for (int k = 0; k < 2; ++k) \
;         acc[ai][bj][m][n] = __builtin_amdgcn_mfma_f32_16x16x32_bf16(Bt[n][k], At[m][k], acc[ai][bj][m][n], 0, 0, 0); __builtin_amdgcn_s_setprio(0); } while (0)
; #define PG8_WAIT_V(n) asm volatile("s_waitcnt vmcnt(" #n ")" ::: "memory")
; #define PG8_WAIT_L(n) asm volatile("s_waitcnt lgkmcnt(" #n ")" ::: "memory")
; #define PG8_BAR __builtin_amdgcn_s_barrier()
; #define PG8_SCHED __builtin_amdgcn_sched_barrier(0)
; template <class Epi, bool ALIGN_EPI = false, bool SP2 = true>
; __device__ __forceinline__ void gemm_phase(LAS unsigned char* lds, const Gemm g, const StaticOrder& S, const Epi& E) {
;     ...
;             PG8_LDA(At, 1, 1); PG8_STAGE(PG8_SB(1, 0), b3, voffB); PG8_STAGE(PG8_SB(1, 1), b3 + hstep, voffB); PG8_STAGE(PG8_SA(1, 0), a3, voffA);
;             PG8_WAIT_V(8); PG8_WAIT_L(0); PG8_BAR; PG8_MMA(1, 0, At, B0); PG8_MMA(1, 1, At, B1); PG8_BAR; PG8_SCHED;
;     ...
;         if (!has_next) break;
; #pragma unroll
;         for (int a = 0; a < 2; ++a)
; #pragma unroll
;             for (int b = 0; b < 2; ++b)
; #pragma unroll
;                 for (int m = 0; m < 4; ++m)
; #pragma unroll
;                     for (int n = 0; n < 2; ++n) acc[a][b][m][n] = (f32x4){0.f, 0.f, 0.f, 0.f};
;         cur = nxt; cA = nA; cB = nB; ++ui;
	s_add_i32 s64, s84, s67
	v_lshl_add_u64 v[162:163], v[162:163], 0, s[24:25]
	s_mov_b32 m0, s64
	ds_read_b128 v[190:193], v151 offset:49152
	ds_read_b128 v[194:197], v151 offset:50176
	ds_read_b128 v[198:201], v151 offset:51200
	ds_read_b128 v[202:205], v151 offset:52224
	ds_read_b128 v[206:209], v151 offset:53248
	ds_read_b128 v[210:213], v151 offset:54272
	ds_read_b128 v[216:219], v151 offset:55296
	ds_read_b128 v[220:223], v151 offset:56320
	global_load_lds_dwordx4 v[162:163], off
	s_add_i32 m0, s64, 0x2000
	s_add_u32 s62, s62, 0x80080
	v_lshl_add_u64 v[162:163], v[224:225], 0, s[24:25]
	s_addc_u32 s63, s63, 0
	s_add_i32 s64, s85, s67
	global_load_lds_dwordx4 v[162:163], off
	v_lshl_add_u64 v[162:163], s[62:63], 0, v[130:131]
	s_mov_b32 m0, s64
	s_nop 0
	global_load_lds_dwordx4 v[162:163], off
	v_lshl_add_u64 v[162:163], s[62:63], 0, v[134:135]
	s_add_i32 m0, s64, 0x2000
	s_nop 0
	global_load_lds_dwordx4 v[162:163], off
	v_lshl_add_u64 v[162:163], v[226:227], 0, s[24:25]
	s_mov_b32 m0, s73
	s_nop 0
	global_load_lds_dwordx4 v[162:163], off
	v_lshl_add_u64 v[162:163], v[228:229], 0, s[24:25]
	s_mov_b32 m0, s74
	s_nop 0
	global_load_lds_dwordx4 v[162:163], off
	s_waitcnt vmcnt(8)
	s_waitcnt lgkmcnt(0)
	s_barrier
	s_waitcnt lgkmcnt(0)
	v_mfma_f32_16x16x32_bf16 v[60:63], v[152:155], v[190:193], v[60:63]
	v_mfma_f32_16x16x32_bf16 v[56:59], v[166:169], v[190:193], v[56:59]
	v_mfma_f32_16x16x32_bf16 v[44:47], v[152:155], v[198:201], v[44:47]
	v_mfma_f32_16x16x32_bf16 v[40:43], v[166:169], v[198:201], v[40:43]
	v_mfma_f32_16x16x32_bf16 v[28:31], v[152:155], v[206:209], v[28:31]
	v_mfma_f32_16x16x32_bf16 v[24:27], v[166:169], v[206:209], v[24:27]
	v_mfma_f32_16x16x32_bf16 v[12:15], v[152:155], v[216:219], v[12:15]
	v_mfma_f32_16x16x32_bf16 v[8:11], v[166:169], v[216:219], v[8:11]
	v_mfma_f32_16x16x32_bf16 v[60:63], v[156:159], v[194:197], v[60:63]
	v_mfma_f32_16x16x32_bf16 v[56:59], v[170:173], v[194:197], v[56:59]
	v_mfma_f32_16x16x32_bf16 v[44:47], v[156:159], v[202:205], v[44:47]
	v_mfma_f32_16x16x32_bf16 v[40:43], v[170:173], v[202:205], v[40:43]
	v_mfma_f32_16x16x32_bf16 v[28:31], v[156:159], v[210:213], v[28:31]
	v_mfma_f32_16x16x32_bf16 v[24:27], v[170:173], v[210:213], v[24:27]
	v_mfma_f32_16x16x32_bf16 v[12:15], v[156:159], v[220:223], v[12:15]
	v_mfma_f32_16x16x32_bf16 v[8:11], v[170:173], v[220:223], v[8:11]
	v_mfma_f32_16x16x32_bf16 v[52:55], v[174:177], v[190:193], v[52:55]
	v_mfma_f32_16x16x32_bf16 v[48:51], v[182:185], v[190:193], v[48:51]
	v_mfma_f32_16x16x32_bf16 v[36:39], v[174:177], v[198:201], v[36:39]
	v_mfma_f32_16x16x32_bf16 v[32:35], v[182:185], v[198:201], v[32:35]
	v_mfma_f32_16x16x32_bf16 v[20:23], v[174:177], v[206:209], v[20:23]
	v_mfma_f32_16x16x32_bf16 v[16:19], v[182:185], v[206:209], v[16:19]
	v_mfma_f32_16x16x32_bf16 v[4:7], v[174:177], v[216:219], v[4:7]
	v_mfma_f32_16x16x32_bf16 v[0:3], v[182:185], v[216:219], v[0:3]
	v_mfma_f32_16x16x32_bf16 v[52:55], v[178:181], v[194:197], v[52:55]
	v_mfma_f32_16x16x32_bf16 v[48:51], v[186:189], v[194:197], v[48:51]
	v_mfma_f32_16x16x32_bf16 v[36:39], v[178:181], v[202:205], v[36:39]
	v_mfma_f32_16x16x32_bf16 v[32:35], v[186:189], v[202:205], v[32:35]
	v_mfma_f32_16x16x32_bf16 v[20:23], v[178:181], v[210:213], v[20:23]
	v_mfma_f32_16x16x32_bf16 v[16:19], v[186:189], v[210:213], v[16:19]
	v_mfma_f32_16x16x32_bf16 v[4:7], v[178:181], v[220:223], v[4:7]
	v_mfma_f32_16x16x32_bf16 v[0:3], v[186:189], v[220:223], v[0:3]
	s_add_i32 s83, s83, 2
	s_add_u32 s60, s60, 0x100
	s_addc_u32 s61, s61, 0
	s_cmp_gt_u32 s83, 29
	s_barrier
	s_cbranch_scc0 .LBB0_325
	s_add_u32 s60, s79, 0xffffff00
	s_addc_u32 s61, s80, -1
	s_andn2_b64 vcc, exec, s[6:7]
	s_cbranch_vccnz .LBB0_328
	v_mov_b32_e32 v0, 0
	s_mov_b32 s22, s26
	s_mov_b32 s18, s28
	s_mov_b64 s[0:1], s[58:59]
	s_mov_b32 s75, s78
	v_mov_b32_e32 v1, v0
	v_mov_b32_e32 v2, v0
	v_mov_b32_e32 v3, v0
	v_mov_b32_e32 v4, v0
	v_mov_b32_e32 v5, v0
	v_mov_b32_e32 v6, v0
	v_mov_b32_e32 v7, v0
	v_mov_b32_e32 v16, v0
	v_mov_b32_e32 v17, v0
	v_mov_b32_e32 v18, v0
	v_mov_b32_e32 v19, v0
	v_mov_b32_e32 v20, v0
	v_mov_b32_e32 v21, v0
	v_mov_b32_e32 v22, v0
	v_mov_b32_e32 v23, v0
	v_mov_b32_e32 v32, v0
	v_mov_b32_e32 v33, v0
	v_mov_b32_e32 v34, v0
	v_mov_b32_e32 v35, v0
	v_mov_b32_e32 v36, v0
	v_mov_b32_e32 v37, v0
	v_mov_b32_e32 v38, v0
	v_mov_b32_e32 v39, v0
	v_mov_b32_e32 v48, v0
	v_mov_b32_e32 v49, v0
	v_mov_b32_e32 v50, v0
	v_mov_b32_e32 v51, v0
	v_mov_b32_e32 v52, v0
	v_mov_b32_e32 v53, v0
	v_mov_b32_e32 v54, v0
	v_mov_b32_e32 v55, v0
	v_mov_b32_e32 v8, v0
	v_mov_b32_e32 v9, v0
	v_mov_b32_e32 v10, v0
	v_mov_b32_e32 v11, v0
	v_mov_b32_e32 v12, v0
	v_mov_b32_e32 v13, v0
	v_mov_b32_e32 v14, v0
	v_mov_b32_e32 v15, v0
	v_mov_b32_e32 v24, v0
	v_mov_b32_e32 v25, v0
	v_mov_b32_e32 v26, v0
	v_mov_b32_e32 v27, v0
	v_mov_b32_e32 v28, v0
	v_mov_b32_e32 v29, v0
	v_mov_b32_e32 v30, v0
	v_mov_b32_e32 v31, v0
	v_mov_b32_e32 v40, v0
	v_mov_b32_e32 v41, v0
	v_mov_b32_e32 v42, v0
	v_mov_b32_e32 v43, v0
	v_mov_b32_e32 v44, v0
	v_mov_b32_e32 v45, v0
	v_mov_b32_e32 v46, v0
	v_mov_b32_e32 v47, v0
	v_mov_b32_e32 v56, v0
	v_mov_b32_e32 v57, v0
	v_mov_b32_e32 v58, v0
	v_mov_b32_e32 v59, v0
	v_mov_b32_e32 v60, v0
	v_mov_b32_e32 v61, v0
	v_mov_b32_e32 v62, v0
	v_mov_b32_e32 v63, v0
	v_mov_b32_e32 v64, v0
	v_mov_b32_e32 v65, v0
	v_mov_b32_e32 v66, v0
	v_mov_b32_e32 v67, v0
	v_mov_b32_e32 v68, v0
	v_mov_b32_e32 v69, v0
	v_mov_b32_e32 v70, v0
	v_mov_b32_e32 v71, v0
	v_mov_b32_e32 v80, v0
	v_mov_b32_e32 v81, v0
	v_mov_b32_e32 v82, v0
	v_mov_b32_e32 v83, v0
	v_mov_b32_e32 v84, v0
	v_mov_b32_e32 v85, v0
	v_mov_b32_e32 v86, v0
	v_mov_b32_e32 v87, v0
	v_mov_b32_e32 v96, v0
	v_mov_b32_e32 v97, v0
	v_mov_b32_e32 v98, v0
	v_mov_b32_e32 v99, v0
	v_mov_b32_e32 v100, v0
	v_mov_b32_e32 v101, v0
	v_mov_b32_e32 v102, v0
	v_mov_b32_e32 v103, v0
	v_mov_b32_e32 v112, v0
	v_mov_b32_e32 v113, v0
	v_mov_b32_e32 v114, v0
	v_mov_b32_e32 v115, v0
	v_mov_b32_e32 v116, v0
	v_mov_b32_e32 v117, v0
	v_mov_b32_e32 v118, v0
	v_mov_b32_e32 v119, v0
	v_mov_b32_e32 v72, v0
	v_mov_b32_e32 v73, v0
	v_mov_b32_e32 v74, v0
	v_mov_b32_e32 v75, v0
	v_mov_b32_e32 v76, v0
	v_mov_b32_e32 v77, v0
	v_mov_b32_e32 v78, v0
	v_mov_b32_e32 v79, v0
	v_mov_b32_e32 v88, v0
	v_mov_b32_e32 v89, v0
	v_mov_b32_e32 v90, v0
	v_mov_b32_e32 v91, v0
	v_mov_b32_e32 v92, v0
	v_mov_b32_e32 v93, v0
	v_mov_b32_e32 v94, v0
	v_mov_b32_e32 v95, v0
	v_mov_b32_e32 v104, v0
	v_mov_b32_e32 v105, v0
	v_mov_b32_e32 v106, v0
	v_mov_b32_e32 v107, v0
	v_mov_b32_e32 v108, v0
	v_mov_b32_e32 v109, v0
	v_mov_b32_e32 v110, v0
	v_mov_b32_e32 v111, v0
	v_mov_b32_e32 v120, v0
	v_mov_b32_e32 v121, v0
	v_mov_b32_e32 v122, v0
	v_mov_b32_e32 v123, v0
	v_mov_b32_e32 v124, v0
	v_mov_b32_e32 v125, v0
	v_mov_b32_e32 v126, v0
	v_mov_b32_e32 v127, v0
	s_andn2_b64 vcc, exec, s[4:5]
	s_cbranch_vccnz .LBB0_329
	s_branch .LBB0_330

; #define PG8_STAGE(bufoff, gbase, voff) do { _Pragma("unroll") for (int _i = 0; _i < 2; ++_i) \
;         __builtin_amdgcn_global_load_lds((const unsigned*)((const char*)(gbase) + (voff)[_i]), (LAS unsigned*)(lds + (bufoff) + ldsw + _i * 8192), 16, 0, 0); } while (0)
; #define PG8_LDA(dst, b, h) do { _Pragma("unroll") for (int m = 0; m < 4; ++m) _Pragma("unroll") for (int k = 0; k < 2; ++k) dst[m][k] = *(const LAS bf16x8*)(lds + PG8_SA(b, h) + aoff + m * 2048 + k * 1024); } while (0)
; #define PG8_LDB(dst, b, h) do { _Pragma("unroll") for (int n = 0; n < 2; ++n) _Pragma("unroll") for (int k = 0; k < 2; ++k) dst[n][k] = *(const LAS bf16x8*)(lds + PG8_SB(b, h) + boff + n * 2048 + k * 1024); } while (0)
; #define PG8_MMA(ai, bj, At, Bt) do { __builtin_amdgcn_s_setprio(1); _Pragma("unroll") for (int m = 0; m < 4; ++m) _Pragma("unroll") for (int n = 0; n < 2; ++n) _Pragma("unroll") for (int k = 0; k < 2; ++k) \
;         acc[ai][bj][m][n] = __builtin_amdgcn_mfma_f32_16x16x32_bf16(Bt[n][k], At[m][k], acc[ai][bj][m][n], 0, 0, 0); __builtin_amdgcn_s_setprio(0); } while (0)
; #define PG8_WAIT_V(n) asm volatile("s_waitcnt vmcnt(" #n ")" ::: "memory")
; #define PG8_WAIT_L(n) asm volatile("s_waitcnt lgkmcnt(" #n ")" ::: "memory")
; #define PG8_BAR __builtin_amdgcn_s_barrier()
; #define PG8_SCHED __builtin_amdgcn_sched_barrier(0)
; template <class Epi, bool ALIGN_EPI = false, bool SP2 = true>
; __device__ __forceinline__ void gemm_phase(LAS unsigned char* lds, const Gemm g, const StaticOrder& S, const Epi& E) {
;     ...
;             PG8_LDB(B0, 0, 0); PG8_LDB(B1, 0, 1); PG8_SCHED; PG8_LDA(At, 0, 0); PG8_STAGE(PG8_SA(1, 1), a1 + hstep, voffA);
;             PG8_WAIT_V(8); PG8_WAIT_L(0); PG8_BAR; PG8_MMA(0, 0, At, B0); PG8_MMA(0, 1, At, B1); PG8_BAR; PG8_SCHED;
;             PG8_LDA(At, 0, 1); PG8_STAGE(PG8_SB(0, 0), b2, voffB); PG8_STAGE(PG8_SB(0, 1), b2 + hstep, voffB); PG8_STAGE(PG8_SA(0, 0), a2, voffA);
;             PG8_WAIT_V(8); PG8_WAIT_L(0); PG8_BAR; PG8_MMA(1, 0, At, B0); PG8_MMA(1, 1, At, B1); PG8_BAR; PG8_SCHED;
.LBB0_441:
	ds_read_b128 v[128:131], v188
	ds_read_b128 v[132:135], v188 offset:1024
	ds_read_b128 v[136:139], v188 offset:2048
	ds_read_b128 v[140:143], v188 offset:3072
	ds_read_b128 v[144:147], v189
	ds_read_b128 v[148:151], v189 offset:1024
	ds_read_b128 v[152:155], v189 offset:2048
	ds_read_b128 v[156:159], v189 offset:3072
	s_add_u32 s56, s36, 0xfff80080
	s_addc_u32 s57, s37, -1
	s_cmp_eq_u32 s79, 28
	s_cselect_b32 s59, s25, s57
	s_cselect_b32 s58, s75, s56
	s_cselect_b32 s57, s23, s78
	s_cselect_b32 s56, s76, s77
	v_lshl_add_u64 v[212:213], s[36:37], 0, v[174:175]
	s_add_i32 m0, s31, 0xc000
	ds_read_b128 v[160:163], v190
	ds_read_b128 v[182:185], v190 offset:1024
	ds_read_b128 v[192:195], v190 offset:2048
	ds_read_b128 v[196:199], v190 offset:3072
	ds_read_b128 v[200:203], v190 offset:4096
	ds_read_b128 v[204:207], v190 offset:5120
	ds_read_b128 v[208:211], v190 offset:6144
	ds_read_b128 v[216:219], v190 offset:7168
	global_load_lds_dwordx4 v[212:213], off
	v_lshl_add_u64 v[212:213], s[36:37], 0, v[176:177]
	s_add_i32 m0, s31, 0xe000
	s_nop 0
	global_load_lds_dwordx4 v[212:213], off
	s_waitcnt vmcnt(8)
	s_waitcnt lgkmcnt(0)
	s_barrier
	s_waitcnt lgkmcnt(0)
	v_mfma_f32_16x16x32_bf16 v[124:127], v[128:131], v[160:163], v[124:127]
	v_mfma_f32_16x16x32_bf16 v[120:123], v[136:139], v[160:163], v[120:123]
	v_mfma_f32_16x16x32_bf16 v[108:111], v[128:131], v[192:195], v[108:111]
	v_mfma_f32_16x16x32_bf16 v[104:107], v[136:139], v[192:195], v[104:107]
	v_mfma_f32_16x16x32_bf16 v[92:95], v[128:131], v[200:203], v[92:95]
	v_mfma_f32_16x16x32_bf16 v[88:91], v[136:139], v[200:203], v[88:91]
	v_mfma_f32_16x16x32_bf16 v[76:79], v[128:131], v[208:211], v[76:79]
	v_mfma_f32_16x16x32_bf16 v[72:75], v[136:139], v[208:211], v[72:75]
	v_mfma_f32_16x16x32_bf16 v[124:127], v[132:135], v[182:185], v[124:127]
	v_mfma_f32_16x16x32_bf16 v[120:123], v[140:143], v[182:185], v[120:123]
	v_mfma_f32_16x16x32_bf16 v[108:111], v[132:135], v[196:199], v[108:111]
	v_mfma_f32_16x16x32_bf16 v[104:107], v[140:143], v[196:199], v[104:107]
	v_mfma_f32_16x16x32_bf16 v[92:95], v[132:135], v[204:207], v[92:95]
	v_mfma_f32_16x16x32_bf16 v[88:91], v[140:143], v[204:207], v[88:91]
	v_mfma_f32_16x16x32_bf16 v[76:79], v[132:135], v[216:219], v[76:79]
	v_mfma_f32_16x16x32_bf16 v[72:75], v[140:143], v[216:219], v[72:75]
	v_mfma_f32_16x16x32_bf16 v[116:119], v[144:147], v[160:163], v[116:119]
	v_mfma_f32_16x16x32_bf16 v[112:115], v[152:155], v[160:163], v[112:115]
	v_mfma_f32_16x16x32_bf16 v[100:103], v[144:147], v[192:195], v[100:103]
	v_mfma_f32_16x16x32_bf16 v[96:99], v[152:155], v[192:195], v[96:99]
	v_mfma_f32_16x16x32_bf16 v[84:87], v[144:147], v[200:203], v[84:87]
	v_mfma_f32_16x16x32_bf16 v[80:83], v[152:155], v[200:203], v[80:83]
	v_mfma_f32_16x16x32_bf16 v[68:71], v[144:147], v[208:211], v[68:71]
	v_mfma_f32_16x16x32_bf16 v[64:67], v[152:155], v[208:211], v[64:67]
	v_mfma_f32_16x16x32_bf16 v[116:119], v[148:151], v[182:185], v[116:119]
	v_mfma_f32_16x16x32_bf16 v[112:115], v[156:159], v[182:185], v[112:115]
	v_mfma_f32_16x16x32_bf16 v[100:103], v[148:151], v[196:199], v[100:103]
	v_mfma_f32_16x16x32_bf16 v[96:99], v[156:159], v[196:199], v[96:99]
	v_mfma_f32_16x16x32_bf16 v[84:87], v[148:151], v[204:207], v[84:87]
	v_mfma_f32_16x16x32_bf16 v[80:83], v[156:159], v[204:207], v[80:83]
	v_mfma_f32_16x16x32_bf16 v[68:71], v[148:151], v[216:219], v[68:71]
	v_mfma_f32_16x16x32_bf16 v[64:67], v[156:159], v[216:219], v[64:67]
	s_barrier
	s_add_i32 s80, s70, s60
	v_lshl_add_u64 v[212:213], s[56:57], 0, v[168:169]
	s_mov_b32 m0, s80
	ds_read_b128 v[160:163], v190 offset:16384
	ds_read_b128 v[182:185], v190 offset:17408
	ds_read_b128 v[192:195], v190 offset:18432
	ds_read_b128 v[196:199], v190 offset:19456
	ds_read_b128 v[200:203], v190 offset:20480
	ds_read_b128 v[204:207], v190 offset:21504
	ds_read_b128 v[208:211], v190 offset:22528
	ds_read_b128 v[216:219], v190 offset:23552
	global_load_lds_dwordx4 v[212:213], off
	s_add_i32 m0, s80, 0x2000
	s_add_u32 s80, s56, 0x80000
	v_lshl_add_u64 v[220:221], s[56:57], 0, v[172:173]
	s_addc_u32 s81, s57, 0
	s_add_i32 s82, s71, s60
	global_load_lds_dwordx4 v[220:221], off
	v_lshl_add_u64 v[222:223], s[80:81], 0, v[168:169]
	s_mov_b32 m0, s82
	v_lshl_add_u64 v[224:225], s[58:59], 0, v[170:171]
	global_load_lds_dwordx4 v[222:223], off
	v_lshl_add_u64 v[222:223], s[80:81], 0, v[172:173]
	s_add_i32 m0, s82, 0x2000
	s_nop 0
	global_load_lds_dwordx4 v[222:223], off
	v_lshl_add_u64 v[222:223], s[58:59], 0, v[166:167]
	s_mov_b32 m0, s31
	s_nop 0
	global_load_lds_dwordx4 v[222:223], off
	s_mov_b32 m0, s61
	s_nop 0
	global_load_lds_dwordx4 v[224:225], off
	s_waitcnt vmcnt(8)
	s_waitcnt lgkmcnt(0)
	s_barrier
; #define PG8_STAGE(bufoff, gbase, voff) do { _Pragma("unroll") for (int _i = 0; _i < 2; ++_i) \
;         __builtin_amdgcn_global_load_lds((const unsigned*)((const char*)(gbase) + (voff)[_i]), (LAS unsigned*)(lds + (bufoff) + ldsw + _i * 8192), 16, 0, 0); } while (0)
; #define PG8_LDA(dst, b, h) do { _Pragma("unroll") for (int m = 0; m < 4; ++m) _Pragma("unroll") for (int k = 0; k < 2; ++k) dst[m][k] = *(const LAS bf16x8*)(lds + PG8_SA(b, h) + aoff + m * 2048 + k * 1024); } while (0)
; #define PG8_LDB(dst, b, h) do { _Pragma("unroll") for (int n = 0; n < 2; ++n) _Pragma("unroll") for (int k = 0; k < 2; ++k) dst[n][k] = *(const LAS bf16x8*)(lds + PG8_SB(b, h) + boff + n * 2048 + k * 1024); } while (0)
; #define PG8_MMA(ai, bj, At, Bt) do { __builtin_amdgcn_s_setprio(1); _Pragma("unroll") for (int m = 0; m < 4; ++m) _Pragma("unroll") for (int n = 0; n < 2; ++n) _Pragma("unroll") for (int k = 0; k < 2; ++k) \
;         acc[ai][bj][m][n] = __builtin_amdgcn_mfma_f32_16x16x32_bf16(Bt[n][k], At[m][k], acc[ai][bj][m][n], 0, 0, 0); __builtin_amdgcn_s_setprio(0); } while (0)
; #define PG8_WAIT_V(n) asm volatile("s_waitcnt vmcnt(" #n ")" ::: "memory")
; #define PG8_WAIT_L(n) asm volatile("s_waitcnt lgkmcnt(" #n ")" ::: "memory")
; #define PG8_BAR __builtin_amdgcn_s_barrier()
; #define PG8_SCHED __builtin_amdgcn_sched_barrier(0)
; template <class Epi, bool ALIGN_EPI = false, bool SP2 = true>
; __device__ __forceinline__ void gemm_phase(LAS unsigned char* lds, const Gemm g, const StaticOrder& S, const Epi& E) {
;     ...
;             PG8_WAIT_V(8); PG8_WAIT_L(0); PG8_BAR; PG8_MMA(1, 0, At, B0); PG8_MMA(1, 1, At, B1); PG8_BAR; PG8_SCHED;
;             PG8_LDB(B0, 1, 0); PG8_LDB(B1, 1, 1); PG8_SCHED; PG8_LDA(At, 1, 0); PG8_STAGE(PG8_SA(0, 1), a2 + hstep, voffA);
;             PG8_WAIT_V(8); PG8_WAIT_L(0); PG8_BAR; PG8_MMA(0, 0, At, B0); PG8_MMA(0, 1, At, B1); PG8_BAR; PG8_SCHED;
	s_waitcnt lgkmcnt(0)
	v_mfma_f32_16x16x32_bf16 v[60:63], v[128:131], v[160:163], v[60:63]
	v_mfma_f32_16x16x32_bf16 v[56:59], v[136:139], v[160:163], v[56:59]
	v_mfma_f32_16x16x32_bf16 v[44:47], v[128:131], v[192:195], v[44:47]
	v_mfma_f32_16x16x32_bf16 v[40:43], v[136:139], v[192:195], v[40:43]
	v_mfma_f32_16x16x32_bf16 v[28:31], v[128:131], v[200:203], v[28:31]
	v_mfma_f32_16x16x32_bf16 v[24:27], v[136:139], v[200:203], v[24:27]
	v_mfma_f32_16x16x32_bf16 v[12:15], v[128:131], v[208:211], v[12:15]
	v_mfma_f32_16x16x32_bf16 v[8:11], v[136:139], v[208:211], v[8:11]
	v_mfma_f32_16x16x32_bf16 v[60:63], v[132:135], v[182:185], v[60:63]
	v_mfma_f32_16x16x32_bf16 v[56:59], v[140:143], v[182:185], v[56:59]
	v_mfma_f32_16x16x32_bf16 v[44:47], v[132:135], v[196:199], v[44:47]
	v_mfma_f32_16x16x32_bf16 v[40:43], v[140:143], v[196:199], v[40:43]
	v_mfma_f32_16x16x32_bf16 v[28:31], v[132:135], v[204:207], v[28:31]
	v_mfma_f32_16x16x32_bf16 v[24:27], v[140:143], v[204:207], v[24:27]
	v_mfma_f32_16x16x32_bf16 v[12:15], v[132:135], v[216:219], v[12:15]
	v_mfma_f32_16x16x32_bf16 v[8:11], v[140:143], v[216:219], v[8:11]
	v_mfma_f32_16x16x32_bf16 v[52:55], v[144:147], v[160:163], v[52:55]
	v_mfma_f32_16x16x32_bf16 v[48:51], v[152:155], v[160:163], v[48:51]
	v_mfma_f32_16x16x32_bf16 v[36:39], v[144:147], v[192:195], v[36:39]
	v_mfma_f32_16x16x32_bf16 v[32:35], v[152:155], v[192:195], v[32:35]
	v_mfma_f32_16x16x32_bf16 v[20:23], v[144:147], v[200:203], v[20:23]
	v_mfma_f32_16x16x32_bf16 v[16:19], v[152:155], v[200:203], v[16:19]
	v_mfma_f32_16x16x32_bf16 v[4:7], v[144:147], v[208:211], v[4:7]
	v_mfma_f32_16x16x32_bf16 v[0:3], v[152:155], v[208:211], v[0:3]
	v_mfma_f32_16x16x32_bf16 v[52:55], v[148:151], v[182:185], v[52:55]
	v_mfma_f32_16x16x32_bf16 v[48:51], v[156:159], v[182:185], v[48:51]
	v_mfma_f32_16x16x32_bf16 v[36:39], v[148:151], v[196:199], v[36:39]
	v_mfma_f32_16x16x32_bf16 v[32:35], v[156:159], v[196:199], v[32:35]
	v_mfma_f32_16x16x32_bf16 v[20:23], v[148:151], v[204:207], v[20:23]
	v_mfma_f32_16x16x32_bf16 v[16:19], v[156:159], v[204:207], v[16:19]
	v_mfma_f32_16x16x32_bf16 v[4:7], v[148:151], v[216:219], v[4:7]
	v_mfma_f32_16x16x32_bf16 v[0:3], v[156:159], v[216:219], v[0:3]
	s_barrier
	s_add_i32 s80, 0, 0x18000
	s_add_i32 s81, 0, 0x1c000
	v_add_u32_e32 v140, s80, v186
	v_add_u32_e32 v156, s81, v186
	ds_read_b128 v[128:131], v140
	ds_read_b128 v[132:135], v140 offset:1024
	ds_read_b128 v[136:139], v140 offset:2048
	ds_read_b128 v[140:143], v140 offset:3072
	ds_read_b128 v[144:147], v156
	ds_read_b128 v[148:151], v156 offset:1024
	ds_read_b128 v[152:155], v156 offset:2048
	ds_read_b128 v[156:159], v156 offset:3072
	s_add_u32 s58, s58, 0x80000
	s_addc_u32 s59, s59, 0
	s_mov_b32 m0, s62
	v_lshl_add_u64 v[226:227], s[58:59], 0, v[166:167]
	ds_read_b128 v[160:163], v190 offset:32768
	ds_read_b128 v[182:185], v190 offset:33792
	ds_read_b128 v[192:195], v190 offset:34816
	ds_read_b128 v[196:199], v190 offset:35840
	ds_read_b128 v[200:203], v190 offset:36864
	ds_read_b128 v[204:207], v190 offset:37888
	ds_read_b128 v[208:211], v190 offset:38912
	ds_read_b128 v[216:219], v190 offset:39936
	global_load_lds_dwordx4 v[226:227], off
	v_lshl_add_u64 v[226:227], s[58:59], 0, v[170:171]
	s_mov_b32 m0, s63
	s_nop 0
	global_load_lds_dwordx4 v[226:227], off
	s_waitcnt vmcnt(8)
	s_waitcnt lgkmcnt(0)
	s_barrier
	s_waitcnt lgkmcnt(0)
	v_mfma_f32_16x16x32_bf16 v[124:127], v[128:131], v[160:163], v[124:127]
	v_mfma_f32_16x16x32_bf16 v[120:123], v[136:139], v[160:163], v[120:123]
	v_mfma_f32_16x16x32_bf16 v[108:111], v[128:131], v[192:195], v[108:111]
	v_mfma_f32_16x16x32_bf16 v[104:107], v[136:139], v[192:195], v[104:107]
	v_mfma_f32_16x16x32_bf16 v[92:95], v[128:131], v[200:203], v[92:95]
	v_mfma_f32_16x16x32_bf16 v[88:91], v[136:139], v[200:203], v[88:91]
	v_mfma_f32_16x16x32_bf16 v[76:79], v[128:131], v[208:211], v[76:79]
	v_mfma_f32_16x16x32_bf16 v[72:75], v[136:139], v[208:211], v[72:75]
	v_mfma_f32_16x16x32_bf16 v[124:127], v[132:135], v[182:185], v[124:127]
	v_mfma_f32_16x16x32_bf16 v[120:123], v[140:143], v[182:185], v[120:123]
	v_mfma_f32_16x16x32_bf16 v[108:111], v[132:135], v[196:199], v[108:111]
	v_mfma_f32_16x16x32_bf16 v[104:107], v[140:143], v[196:199], v[104:107]
	v_mfma_f32_16x16x32_bf16 v[92:95], v[132:135], v[204:207], v[92:95]
	v_mfma_f32_16x16x32_bf16 v[88:91], v[140:143], v[204:207], v[88:91]
	v_mfma_f32_16x16x32_bf16 v[76:79], v[132:135], v[216:219], v[76:79]
	v_mfma_f32_16x16x32_bf16 v[72:75], v[140:143], v[216:219], v[72:75]
	v_mfma_f32_16x16x32_bf16 v[116:119], v[144:147], v[160:163], v[116:119]
	v_mfma_f32_16x16x32_bf16 v[112:115], v[152:155], v[160:163], v[112:115]
	v_mfma_f32_16x16x32_bf16 v[100:103], v[144:147], v[192:195], v[100:103]
	v_mfma_f32_16x16x32_bf16 v[96:99], v[152:155], v[192:195], v[96:99]
	v_mfma_f32_16x16x32_bf16 v[84:87], v[144:147], v[200:203], v[84:87]
	v_mfma_f32_16x16x32_bf16 v[80:83], v[152:155], v[200:203], v[80:83]
	v_mfma_f32_16x16x32_bf16 v[68:71], v[144:147], v[208:211], v[68:71]
	v_mfma_f32_16x16x32_bf16 v[64:67], v[152:155], v[208:211], v[64:67]
	v_mfma_f32_16x16x32_bf16 v[116:119], v[148:151], v[182:185], v[116:119]
	v_mfma_f32_16x16x32_bf16 v[112:115], v[156:159], v[182:185], v[112:115]
	v_mfma_f32_16x16x32_bf16 v[100:103], v[148:151], v[196:199], v[100:103]
	v_mfma_f32_16x16x32_bf16 v[96:99], v[156:159], v[196:199], v[96:99]
	v_mfma_f32_16x16x32_bf16 v[84:87], v[148:151], v[204:207], v[84:87]
	v_mfma_f32_16x16x32_bf16 v[80:83], v[156:159], v[204:207], v[80:83]
	v_mfma_f32_16x16x32_bf16 v[68:71], v[148:151], v[216:219], v[68:71]
	v_mfma_f32_16x16x32_bf16 v[64:67], v[156:159], v[216:219], v[64:67]
	s_barrier
; #define PG8_STAGE(bufoff, gbase, voff) do { _Pragma("unroll") for (int _i = 0; _i < 2; ++_i) \
;         __builtin_amdgcn_global_load_lds((const unsigned*)((const char*)(gbase) + (voff)[_i]), (LAS unsigned*)(lds + (bufoff) + ldsw + _i * 8192), 16, 0, 0); } while (0)
; #define PG8_LDA(dst, b, h) do { _Pragma("unroll") for (int m = 0; m < 4; ++m) _Pragma("unroll") for (int k = 0; k < 2; ++k) dst[m][k] = *(const LAS bf16x8*)(lds + PG8_SA(b, h) + aoff + m * 2048 + k * 1024); } while (0)
; #define PG8_MMA(ai, bj, At, Bt) do { __builtin_amdgcn_s_setprio(1); _Pragma("unroll") for (int m = 0; m < 4; ++m) _Pragma("unroll") for (int n = 0; n < 2; ++n) _Pragma("unroll") for (int k = 0; k < 2; ++k) \
;         acc[ai][bj][m][n] = __builtin_amdgcn_mfma_f32_16x16x32_bf16(Bt[n][k], At[m][k], acc[ai][bj][m][n], 0, 0, 0); __builtin_amdgcn_s_setprio(0); } while (0)
; #define PG8_WAIT_V(n) asm volatile("s_waitcnt vmcnt(" #n ")" ::: "memory")
; #define PG8_WAIT_L(n) asm volatile("s_waitcnt lgkmcnt(" #n ")" ::: "memory")
; #define PG8_BAR __builtin_amdgcn_s_barrier()
; #define PG8_SCHED __builtin_amdgcn_sched_barrier(0)
; template <class Epi, bool ALIGN_EPI = false, bool SP2 = true>
; __device__ __forceinline__ void gemm_phase(LAS unsigned char* lds, const Gemm g, const StaticOrder& S, const Epi& E) {
;     ...
;         for (int t = 0; t < nt; t += 2) {
;             const bool last = (t == nt - 2);
;             const char* a1 = cA + (size_t)(t + 1) * kstep;
;             const char* a2 = last ? nA : cA + (size_t)(t + 2) * kstep; const char* b2 = last ? nB : cB + (size_t)(t + 2) * kstep;
;     ...
;             PG8_LDA(At, 1, 1); PG8_STAGE(PG8_SB(1, 0), b3, voffB); PG8_STAGE(PG8_SB(1, 1), b3 + hstep, voffB); PG8_STAGE(PG8_SA(1, 0), a3, voffA);
;             PG8_WAIT_V(8); PG8_WAIT_L(0); PG8_BAR; PG8_MMA(1, 0, At, B0); PG8_MMA(1, 1, At, B1); PG8_BAR; PG8_SCHED;
	s_add_i32 s58, s80, s60
	v_lshl_add_u64 v[212:213], v[212:213], 0, s[16:17]
	s_mov_b32 m0, s58
	ds_read_b128 v[160:163], v190 offset:49152
	ds_read_b128 v[182:185], v190 offset:50176
	ds_read_b128 v[192:195], v190 offset:51200
	ds_read_b128 v[196:199], v190 offset:52224
	ds_read_b128 v[200:203], v190 offset:53248
	ds_read_b128 v[204:207], v190 offset:54272
	ds_read_b128 v[208:211], v190 offset:55296
	ds_read_b128 v[216:219], v190 offset:56320
	global_load_lds_dwordx4 v[212:213], off
	s_add_i32 m0, s58, 0x2000
	s_add_u32 s56, s56, 0x80080
	v_lshl_add_u64 v[212:213], v[220:221], 0, s[16:17]
	s_addc_u32 s57, s57, 0
	s_add_i32 s58, s81, s60
	global_load_lds_dwordx4 v[212:213], off
	v_lshl_add_u64 v[212:213], s[56:57], 0, v[168:169]
	s_mov_b32 m0, s58
	s_nop 0
	global_load_lds_dwordx4 v[212:213], off
	v_lshl_add_u64 v[212:213], s[56:57], 0, v[172:173]
	s_add_i32 m0, s58, 0x2000
	s_nop 0
	global_load_lds_dwordx4 v[212:213], off
	v_lshl_add_u64 v[212:213], v[222:223], 0, s[16:17]
	s_mov_b32 m0, s66
	s_nop 0
	global_load_lds_dwordx4 v[212:213], off
	v_lshl_add_u64 v[212:213], v[224:225], 0, s[16:17]
	s_mov_b32 m0, s67
	s_nop 0
	global_load_lds_dwordx4 v[212:213], off
	s_waitcnt vmcnt(8)
	s_waitcnt lgkmcnt(0)
	s_barrier
	s_waitcnt lgkmcnt(0)
	v_mfma_f32_16x16x32_bf16 v[60:63], v[128:131], v[160:163], v[60:63]
	v_mfma_f32_16x16x32_bf16 v[56:59], v[136:139], v[160:163], v[56:59]
	v_mfma_f32_16x16x32_bf16 v[44:47], v[128:131], v[192:195], v[44:47]
	v_mfma_f32_16x16x32_bf16 v[40:43], v[136:139], v[192:195], v[40:43]
	v_mfma_f32_16x16x32_bf16 v[28:31], v[128:131], v[200:203], v[28:31]
	v_mfma_f32_16x16x32_bf16 v[24:27], v[136:139], v[200:203], v[24:27]
	v_mfma_f32_16x16x32_bf16 v[12:15], v[128:131], v[208:211], v[12:15]
	v_mfma_f32_16x16x32_bf16 v[8:11], v[136:139], v[208:211], v[8:11]
	v_mfma_f32_16x16x32_bf16 v[60:63], v[132:135], v[182:185], v[60:63]
	v_mfma_f32_16x16x32_bf16 v[56:59], v[140:143], v[182:185], v[56:59]
	v_mfma_f32_16x16x32_bf16 v[44:47], v[132:135], v[196:199], v[44:47]
	v_mfma_f32_16x16x32_bf16 v[40:43], v[140:143], v[196:199], v[40:43]
	v_mfma_f32_16x16x32_bf16 v[28:31], v[132:135], v[204:207], v[28:31]
	v_mfma_f32_16x16x32_bf16 v[24:27], v[140:143], v[204:207], v[24:27]
	v_mfma_f32_16x16x32_bf16 v[12:15], v[132:135], v[216:219], v[12:15]
	v_mfma_f32_16x16x32_bf16 v[8:11], v[140:143], v[216:219], v[8:11]
	v_mfma_f32_16x16x32_bf16 v[52:55], v[144:147], v[160:163], v[52:55]
	v_mfma_f32_16x16x32_bf16 v[48:51], v[152:155], v[160:163], v[48:51]
	v_mfma_f32_16x16x32_bf16 v[36:39], v[144:147], v[192:195], v[36:39]
	v_mfma_f32_16x16x32_bf16 v[32:35], v[152:155], v[192:195], v[32:35]
	v_mfma_f32_16x16x32_bf16 v[20:23], v[144:147], v[200:203], v[20:23]
	v_mfma_f32_16x16x32_bf16 v[16:19], v[152:155], v[200:203], v[16:19]
	v_mfma_f32_16x16x32_bf16 v[4:7], v[144:147], v[208:211], v[4:7]
	v_mfma_f32_16x16x32_bf16 v[0:3], v[152:155], v[208:211], v[0:3]
	v_mfma_f32_16x16x32_bf16 v[52:55], v[148:151], v[182:185], v[52:55]
	v_mfma_f32_16x16x32_bf16 v[48:51], v[156:159], v[182:185], v[48:51]
	v_mfma_f32_16x16x32_bf16 v[36:39], v[148:151], v[196:199], v[36:39]
	v_mfma_f32_16x16x32_bf16 v[32:35], v[156:159], v[196:199], v[32:35]
	v_mfma_f32_16x16x32_bf16 v[20:23], v[148:151], v[204:207], v[20:23]
	v_mfma_f32_16x16x32_bf16 v[16:19], v[156:159], v[204:207], v[16:19]
	v_mfma_f32_16x16x32_bf16 v[4:7], v[148:151], v[216:219], v[4:7]
	v_mfma_f32_16x16x32_bf16 v[0:3], v[156:159], v[216:219], v[0:3]
	s_add_i32 s79, s79, 2
	s_add_u32 s36, s36, 0x100
	s_addc_u32 s37, s37, 0
	s_add_u32 s77, s77, 0x100
	s_addc_u32 s78, s78, 0
	s_cmp_gt_u32 s79, 29
	s_barrier
	s_cbranch_scc0 .LBB0_441
	s_and_b64 vcc, exec, s[18:19]
	s_cbranch_vccz .LBB0_444
	s_barrier

; #define PG8_STAGE(bufoff, gbase, voff) do { _Pragma("unroll") for (int _i = 0; _i < 2; ++_i) \
;         __builtin_amdgcn_global_load_lds((const unsigned*)((const char*)(gbase) + (voff)[_i]), (LAS unsigned*)(lds + (bufoff) + ldsw + _i * 8192), 16, 0, 0); } while (0)
; #define PG8_LDA(dst, b, h) do { _Pragma("unroll") for (int m = 0; m < 4; ++m) _Pragma("unroll") for (int k = 0; k < 2; ++k) dst[m][k] = *(const LAS bf16x8*)(lds + PG8_SA(b, h) + aoff + m * 2048 + k * 1024); } while (0)
; #define PG8_LDB(dst, b, h) do { _Pragma("unroll") for (int n = 0; n < 2; ++n) _Pragma("unroll") for (int k = 0; k < 2; ++k) dst[n][k] = *(const LAS bf16x8*)(lds + PG8_SB(b, h) + boff + n * 2048 + k * 1024); } while (0)
; #define PG8_MMA(ai, bj, At, Bt) do { __builtin_amdgcn_s_setprio(1); _Pragma("unroll") for (int m = 0; m < 4; ++m) _Pragma("unroll") for (int n = 0; n < 2; ++n) _Pragma("unroll") for (int k = 0; k < 2; ++k) \
;         acc[ai][bj][m][n] = __builtin_amdgcn_mfma_f32_16x16x32_bf16(Bt[n][k], At[m][k], acc[ai][bj][m][n], 0, 0, 0); __builtin_amdgcn_s_setprio(0); } while (0)
; #define PG8_WAIT_V(n) asm volatile("s_waitcnt vmcnt(" #n ")" ::: "memory")
; #define PG8_WAIT_L(n) asm volatile("s_waitcnt lgkmcnt(" #n ")" ::: "memory")
; #define PG8_BAR __builtin_amdgcn_s_barrier()
; #define PG8_SCHED __builtin_amdgcn_sched_barrier(0)
; template <class Epi, bool ALIGN_EPI = false, bool SP2 = true>
; __device__ __forceinline__ void gemm_phase(LAS unsigned char* lds, const Gemm g, const StaticOrder& S, const Epi& E) {
;     ...
;             PG8_LDB(B0, 0, 0); PG8_LDB(B1, 0, 1); PG8_SCHED; PG8_LDA(At, 0, 0); PG8_STAGE(PG8_SA(1, 1), a1 + hstep, voffA);
;             PG8_WAIT_V(8); PG8_WAIT_L(0); PG8_BAR; PG8_MMA(0, 0, At, B0); PG8_MMA(0, 1, At, B1); PG8_BAR; PG8_SCHED;
;             PG8_LDA(At, 0, 1); PG8_STAGE(PG8_SB(0, 0), b2, voffB); PG8_STAGE(PG8_SB(0, 1), b2 + hstep, voffB); PG8_STAGE(PG8_SA(0, 0), a2, voffA);
;             PG8_WAIT_V(8); PG8_WAIT_L(0); PG8_BAR; PG8_MMA(1, 0, At, B0); PG8_MMA(1, 1, At, B1); PG8_BAR; PG8_SCHED;
.LBB0_518:
	ds_read_b128 v[148:151], v166
	s_waitcnt lgkmcnt(0)
	ds_read_b128 v[152:155], v166 offset:1024
	ds_read_b128 v[156:159], v166 offset:2048
	ds_read_b128 v[170:173], v166 offset:3072
	ds_read_b128 v[174:177], v167
	ds_read_b128 v[178:181], v167 offset:1024
	ds_read_b128 v[182:185], v167 offset:2048
	ds_read_b128 v[186:189], v167 offset:3072
	s_add_u32 s60, s10, 0xfff80080
	s_addc_u32 s61, s11, -1
	s_cmp_eq_u32 s82, 28
	s_cselect_b32 s63, s9, s61
	s_cselect_b32 s62, s37, s60
	s_cselect_b32 s61, s31, s81
	s_cselect_b32 s60, s79, s80
	v_lshl_add_u64 v[160:161], s[10:11], 0, v[138:139]
	s_add_i32 m0, s65, 0xc000
	ds_read_b128 v[190:193], v168
	ds_read_b128 v[194:197], v168 offset:1024
	ds_read_b128 v[198:201], v168 offset:2048
	ds_read_b128 v[202:205], v168 offset:3072
	ds_read_b128 v[206:209], v168 offset:4096
	ds_read_b128 v[210:213], v168 offset:5120
	ds_read_b128 v[216:219], v168 offset:6144
	ds_read_b128 v[220:223], v168 offset:7168
	global_load_lds_dwordx4 v[160:161], off
	v_lshl_add_u64 v[160:161], s[10:11], 0, v[140:141]
	s_add_i32 m0, s65, 0xe000
	s_nop 0
	global_load_lds_dwordx4 v[160:161], off
	s_waitcnt vmcnt(8)
	s_waitcnt lgkmcnt(0)
	s_barrier
	s_waitcnt lgkmcnt(0)
	v_mfma_f32_16x16x32_bf16 v[124:127], v[148:151], v[190:193], v[124:127]
	v_mfma_f32_16x16x32_bf16 v[92:95], v[156:159], v[190:193], v[92:95]
	v_mfma_f32_16x16x32_bf16 v[120:123], v[148:151], v[198:201], v[120:123]
	v_mfma_f32_16x16x32_bf16 v[88:91], v[156:159], v[198:201], v[88:91]
	v_mfma_f32_16x16x32_bf16 v[116:119], v[148:151], v[206:209], v[116:119]
	v_mfma_f32_16x16x32_bf16 v[84:87], v[156:159], v[206:209], v[84:87]
	v_mfma_f32_16x16x32_bf16 v[112:115], v[148:151], v[216:219], v[112:115]
	v_mfma_f32_16x16x32_bf16 v[80:83], v[156:159], v[216:219], v[80:83]
	v_mfma_f32_16x16x32_bf16 v[124:127], v[152:155], v[194:197], v[124:127]
	v_mfma_f32_16x16x32_bf16 v[92:95], v[170:173], v[194:197], v[92:95]
	v_mfma_f32_16x16x32_bf16 v[120:123], v[152:155], v[202:205], v[120:123]
	v_mfma_f32_16x16x32_bf16 v[88:91], v[170:173], v[202:205], v[88:91]
	v_mfma_f32_16x16x32_bf16 v[116:119], v[152:155], v[210:213], v[116:119]
	v_mfma_f32_16x16x32_bf16 v[84:87], v[170:173], v[210:213], v[84:87]
	v_mfma_f32_16x16x32_bf16 v[112:115], v[152:155], v[220:223], v[112:115]
	v_mfma_f32_16x16x32_bf16 v[80:83], v[170:173], v[220:223], v[80:83]
	v_mfma_f32_16x16x32_bf16 v[60:63], v[174:177], v[190:193], v[60:63]
	v_mfma_f32_16x16x32_bf16 v[28:31], v[182:185], v[190:193], v[28:31]
	v_mfma_f32_16x16x32_bf16 v[56:59], v[174:177], v[198:201], v[56:59]
	v_mfma_f32_16x16x32_bf16 v[24:27], v[182:185], v[198:201], v[24:27]
	v_mfma_f32_16x16x32_bf16 v[52:55], v[174:177], v[206:209], v[52:55]
	v_mfma_f32_16x16x32_bf16 v[20:23], v[182:185], v[206:209], v[20:23]
	v_mfma_f32_16x16x32_bf16 v[48:51], v[174:177], v[216:219], v[48:51]
	v_mfma_f32_16x16x32_bf16 v[16:19], v[182:185], v[216:219], v[16:19]
	v_mfma_f32_16x16x32_bf16 v[60:63], v[178:181], v[194:197], v[60:63]
	v_mfma_f32_16x16x32_bf16 v[28:31], v[186:189], v[194:197], v[28:31]
	v_mfma_f32_16x16x32_bf16 v[56:59], v[178:181], v[202:205], v[56:59]
	v_mfma_f32_16x16x32_bf16 v[24:27], v[186:189], v[202:205], v[24:27]
	v_mfma_f32_16x16x32_bf16 v[52:55], v[178:181], v[210:213], v[52:55]
	v_mfma_f32_16x16x32_bf16 v[20:23], v[186:189], v[210:213], v[20:23]
	v_mfma_f32_16x16x32_bf16 v[48:51], v[178:181], v[220:223], v[48:51]
	v_mfma_f32_16x16x32_bf16 v[16:19], v[186:189], v[220:223], v[16:19]
	s_barrier
	s_add_i32 s83, s75, s64
	v_lshl_add_u64 v[160:161], s[60:61], 0, v[130:131]
	s_mov_b32 m0, s83
	ds_read_b128 v[190:193], v168 offset:16384
	ds_read_b128 v[194:197], v168 offset:17408
	ds_read_b128 v[198:201], v168 offset:18432
	ds_read_b128 v[202:205], v168 offset:19456
	ds_read_b128 v[206:209], v168 offset:20480
	ds_read_b128 v[210:213], v168 offset:21504
	ds_read_b128 v[216:219], v168 offset:22528
	ds_read_b128 v[220:223], v168 offset:23552
	global_load_lds_dwordx4 v[160:161], off
	s_add_i32 m0, s83, 0x2000
	s_add_u32 s84, s60, 0x80000
	v_lshl_add_u64 v[224:225], s[60:61], 0, v[134:135]
	s_addc_u32 s85, s61, 0
	s_add_i32 s83, s77, s64
	global_load_lds_dwordx4 v[224:225], off
	v_lshl_add_u64 v[226:227], s[84:85], 0, v[130:131]
	s_mov_b32 m0, s83
	v_lshl_add_u64 v[228:229], s[62:63], 0, v[132:133]
	global_load_lds_dwordx4 v[226:227], off
	v_lshl_add_u64 v[226:227], s[84:85], 0, v[134:135]
	s_add_i32 m0, s83, 0x2000
	s_nop 0
	global_load_lds_dwordx4 v[226:227], off
	v_lshl_add_u64 v[226:227], s[62:63], 0, v[128:129]
	s_mov_b32 m0, s65
	s_nop 0
	global_load_lds_dwordx4 v[226:227], off
	s_mov_b32 m0, s66
	s_nop 0
	global_load_lds_dwordx4 v[228:229], off
	s_waitcnt vmcnt(8)
	s_waitcnt lgkmcnt(0)
	s_barrier
; #define PG8_STAGE(bufoff, gbase, voff) do { _Pragma("unroll") for (int _i = 0; _i < 2; ++_i) \
;         __builtin_amdgcn_global_load_lds((const unsigned*)((const char*)(gbase) + (voff)[_i]), (LAS unsigned*)(lds + (bufoff) + ldsw + _i * 8192), 16, 0, 0); } while (0)
; #define PG8_LDA(dst, b, h) do { _Pragma("unroll") for (int m = 0; m < 4; ++m) _Pragma("unroll") for (int k = 0; k < 2; ++k) dst[m][k] = *(const LAS bf16x8*)(lds + PG8_SA(b, h) + aoff + m * 2048 + k * 1024); } while (0)
; #define PG8_LDB(dst, b, h) do { _Pragma("unroll") for (int n = 0; n < 2; ++n) _Pragma("unroll") for (int k = 0; k < 2; ++k) dst[n][k] = *(const LAS bf16x8*)(lds + PG8_SB(b, h) + boff + n * 2048 + k * 1024); } while (0)
; #define PG8_MMA(ai, bj, At, Bt) do { __builtin_amdgcn_s_setprio(1); _Pragma("unroll") for (int m = 0; m < 4; ++m) _Pragma("unroll") for (int n = 0; n < 2; ++n) _Pragma("unroll") for (int k = 0; k < 2; ++k) \
;         acc[ai][bj][m][n] = __builtin_amdgcn_mfma_f32_16x16x32_bf16(Bt[n][k], At[m][k], acc[ai][bj][m][n], 0, 0, 0); __builtin_amdgcn_s_setprio(0); } while (0)
; #define PG8_WAIT_V(n) asm volatile("s_waitcnt vmcnt(" #n ")" ::: "memory")
; #define PG8_WAIT_L(n) asm volatile("s_waitcnt lgkmcnt(" #n ")" ::: "memory")
; #define PG8_BAR __builtin_amdgcn_s_barrier()
; #define PG8_SCHED __builtin_amdgcn_sched_barrier(0)
; template <class Epi, bool ALIGN_EPI = false, bool SP2 = true>
; __device__ __forceinline__ void gemm_phase(LAS unsigned char* lds, const Gemm g, const StaticOrder& S, const Epi& E) {
;     ...
;             PG8_WAIT_V(8); PG8_WAIT_L(0); PG8_BAR; PG8_MMA(1, 0, At, B0); PG8_MMA(1, 1, At, B1); PG8_BAR; PG8_SCHED;
;             PG8_LDB(B0, 1, 0); PG8_LDB(B1, 1, 1); PG8_SCHED; PG8_LDA(At, 1, 0); PG8_STAGE(PG8_SA(0, 1), a2 + hstep, voffA);
;             PG8_WAIT_V(8); PG8_WAIT_L(0); PG8_BAR; PG8_MMA(0, 0, At, B0); PG8_MMA(0, 1, At, B1); PG8_BAR; PG8_SCHED;
	s_waitcnt lgkmcnt(0)
	v_mfma_f32_16x16x32_bf16 v[108:111], v[148:151], v[190:193], v[108:111]
	v_mfma_f32_16x16x32_bf16 v[76:79], v[156:159], v[190:193], v[76:79]
	v_mfma_f32_16x16x32_bf16 v[104:107], v[148:151], v[198:201], v[104:107]
	v_mfma_f32_16x16x32_bf16 v[72:75], v[156:159], v[198:201], v[72:75]
	v_mfma_f32_16x16x32_bf16 v[100:103], v[148:151], v[206:209], v[100:103]
	v_mfma_f32_16x16x32_bf16 v[68:71], v[156:159], v[206:209], v[68:71]
	v_mfma_f32_16x16x32_bf16 v[96:99], v[148:151], v[216:219], v[96:99]
	v_mfma_f32_16x16x32_bf16 v[64:67], v[156:159], v[216:219], v[64:67]
	v_mfma_f32_16x16x32_bf16 v[108:111], v[152:155], v[194:197], v[108:111]
	v_mfma_f32_16x16x32_bf16 v[76:79], v[170:173], v[194:197], v[76:79]
	v_mfma_f32_16x16x32_bf16 v[104:107], v[152:155], v[202:205], v[104:107]
	v_mfma_f32_16x16x32_bf16 v[72:75], v[170:173], v[202:205], v[72:75]
	v_mfma_f32_16x16x32_bf16 v[100:103], v[152:155], v[210:213], v[100:103]
	v_mfma_f32_16x16x32_bf16 v[68:71], v[170:173], v[210:213], v[68:71]
	v_mfma_f32_16x16x32_bf16 v[96:99], v[152:155], v[220:223], v[96:99]
	v_mfma_f32_16x16x32_bf16 v[64:67], v[170:173], v[220:223], v[64:67]
	v_mfma_f32_16x16x32_bf16 v[44:47], v[174:177], v[190:193], v[44:47]
	v_mfma_f32_16x16x32_bf16 v[12:15], v[182:185], v[190:193], v[12:15]
	v_mfma_f32_16x16x32_bf16 v[40:43], v[174:177], v[198:201], v[40:43]
	v_mfma_f32_16x16x32_bf16 v[8:11], v[182:185], v[198:201], v[8:11]
	v_mfma_f32_16x16x32_bf16 v[36:39], v[174:177], v[206:209], v[36:39]
	v_mfma_f32_16x16x32_bf16 v[4:7], v[182:185], v[206:209], v[4:7]
	v_mfma_f32_16x16x32_bf16 v[32:35], v[174:177], v[216:219], v[32:35]
	v_mfma_f32_16x16x32_bf16 v[0:3], v[182:185], v[216:219], v[0:3]
	v_mfma_f32_16x16x32_bf16 v[44:47], v[178:181], v[194:197], v[44:47]
	v_mfma_f32_16x16x32_bf16 v[12:15], v[186:189], v[194:197], v[12:15]
	v_mfma_f32_16x16x32_bf16 v[40:43], v[178:181], v[202:205], v[40:43]
	v_mfma_f32_16x16x32_bf16 v[8:11], v[186:189], v[202:205], v[8:11]
	v_mfma_f32_16x16x32_bf16 v[36:39], v[178:181], v[210:213], v[36:39]
	v_mfma_f32_16x16x32_bf16 v[4:7], v[186:189], v[210:213], v[4:7]
	v_mfma_f32_16x16x32_bf16 v[32:35], v[178:181], v[220:223], v[32:35]
	v_mfma_f32_16x16x32_bf16 v[0:3], v[186:189], v[220:223], v[0:3]
	s_barrier
	s_add_i32 s83, 0, 0x18000
	v_add_u32_e32 v136, s83, v163
	s_add_i32 s84, 0, 0x1c000
	ds_read_b128 v[148:151], v136
	ds_read_b128 v[152:155], v136 offset:1024
	ds_read_b128 v[156:159], v136 offset:2048
	ds_read_b128 v[170:173], v136 offset:3072
	v_add_u32_e32 v136, s84, v163
	ds_read_b128 v[174:177], v136
	ds_read_b128 v[178:181], v136 offset:1024
	ds_read_b128 v[182:185], v136 offset:2048
	ds_read_b128 v[186:189], v136 offset:3072
	s_add_u32 s62, s62, 0x80000
	s_addc_u32 s63, s63, 0
	s_mov_b32 m0, s67
	v_lshl_add_u64 v[230:231], s[62:63], 0, v[128:129]
	ds_read_b128 v[190:193], v168 offset:32768
	ds_read_b128 v[194:197], v168 offset:33792
	ds_read_b128 v[198:201], v168 offset:34816
	ds_read_b128 v[202:205], v168 offset:35840
	ds_read_b128 v[206:209], v168 offset:36864
	ds_read_b128 v[210:213], v168 offset:37888
	ds_read_b128 v[216:219], v168 offset:38912
	ds_read_b128 v[220:223], v168 offset:39936
	global_load_lds_dwordx4 v[230:231], off
	v_lshl_add_u64 v[230:231], s[62:63], 0, v[132:133]
	s_mov_b32 m0, s68
	s_nop 0
	global_load_lds_dwordx4 v[230:231], off
	s_waitcnt vmcnt(8)
	s_waitcnt lgkmcnt(0)
	s_barrier
	s_waitcnt lgkmcnt(0)
	v_mfma_f32_16x16x32_bf16 v[124:127], v[148:151], v[190:193], v[124:127]
	v_mfma_f32_16x16x32_bf16 v[92:95], v[156:159], v[190:193], v[92:95]
	v_mfma_f32_16x16x32_bf16 v[120:123], v[148:151], v[198:201], v[120:123]
	v_mfma_f32_16x16x32_bf16 v[88:91], v[156:159], v[198:201], v[88:91]
	v_mfma_f32_16x16x32_bf16 v[116:119], v[148:151], v[206:209], v[116:119]
	v_mfma_f32_16x16x32_bf16 v[84:87], v[156:159], v[206:209], v[84:87]
	v_mfma_f32_16x16x32_bf16 v[112:115], v[148:151], v[216:219], v[112:115]
	v_mfma_f32_16x16x32_bf16 v[80:83], v[156:159], v[216:219], v[80:83]
	v_mfma_f32_16x16x32_bf16 v[124:127], v[152:155], v[194:197], v[124:127]
	v_mfma_f32_16x16x32_bf16 v[92:95], v[170:173], v[194:197], v[92:95]
	v_mfma_f32_16x16x32_bf16 v[120:123], v[152:155], v[202:205], v[120:123]
	v_mfma_f32_16x16x32_bf16 v[88:91], v[170:173], v[202:205], v[88:91]
	v_mfma_f32_16x16x32_bf16 v[116:119], v[152:155], v[210:213], v[116:119]
	v_mfma_f32_16x16x32_bf16 v[84:87], v[170:173], v[210:213], v[84:87]
	v_mfma_f32_16x16x32_bf16 v[112:115], v[152:155], v[220:223], v[112:115]
	v_mfma_f32_16x16x32_bf16 v[80:83], v[170:173], v[220:223], v[80:83]
	v_mfma_f32_16x16x32_bf16 v[60:63], v[174:177], v[190:193], v[60:63]
	v_mfma_f32_16x16x32_bf16 v[28:31], v[182:185], v[190:193], v[28:31]
	v_mfma_f32_16x16x32_bf16 v[56:59], v[174:177], v[198:201], v[56:59]
	v_mfma_f32_16x16x32_bf16 v[24:27], v[182:185], v[198:201], v[24:27]
	v_mfma_f32_16x16x32_bf16 v[52:55], v[174:177], v[206:209], v[52:55]
	v_mfma_f32_16x16x32_bf16 v[20:23], v[182:185], v[206:209], v[20:23]
	v_mfma_f32_16x16x32_bf16 v[48:51], v[174:177], v[216:219], v[48:51]
	v_mfma_f32_16x16x32_bf16 v[16:19], v[182:185], v[216:219], v[16:19]
	v_mfma_f32_16x16x32_bf16 v[60:63], v[178:181], v[194:197], v[60:63]
	v_mfma_f32_16x16x32_bf16 v[28:31], v[186:189], v[194:197], v[28:31]
	v_mfma_f32_16x16x32_bf16 v[56:59], v[178:181], v[202:205], v[56:59]
	v_mfma_f32_16x16x32_bf16 v[24:27], v[186:189], v[202:205], v[24:27]
	v_mfma_f32_16x16x32_bf16 v[52:55], v[178:181], v[210:213], v[52:55]
	v_mfma_f32_16x16x32_bf16 v[20:23], v[186:189], v[210:213], v[20:23]
	v_mfma_f32_16x16x32_bf16 v[48:51], v[178:181], v[220:223], v[48:51]
	v_mfma_f32_16x16x32_bf16 v[16:19], v[186:189], v[220:223], v[16:19]
	s_barrier
; #define PG8_STAGE(bufoff, gbase, voff) do { _Pragma("unroll") for (int _i = 0; _i < 2; ++_i) \
;         __builtin_amdgcn_global_load_lds((const unsigned*)((const char*)(gbase) + (voff)[_i]), (LAS unsigned*)(lds + (bufoff) + ldsw + _i * 8192), 16, 0, 0); } while (0)
; #define PG8_LDA(dst, b, h) do { _Pragma("unroll") for (int m = 0; m < 4; ++m) _Pragma("unroll") for (int k = 0; k < 2; ++k) dst[m][k] = *(const LAS bf16x8*)(lds + PG8_SA(b, h) + aoff + m * 2048 + k * 1024); } while (0)
; #define PG8_MMA(ai, bj, At, Bt) do { __builtin_amdgcn_s_setprio(1); _Pragma("unroll") for (int m = 0; m < 4; ++m) _Pragma("unroll") for (int n = 0; n < 2; ++n) _Pragma("unroll") for (int k = 0; k < 2; ++k) \
;         acc[ai][bj][m][n] = __builtin_amdgcn_mfma_f32_16x16x32_bf16(Bt[n][k], At[m][k], acc[ai][bj][m][n], 0, 0, 0); __builtin_amdgcn_s_setprio(0); } while (0)
; #define PG8_WAIT_V(n) asm volatile("s_waitcnt vmcnt(" #n ")" ::: "memory")
; #define PG8_WAIT_L(n) asm volatile("s_waitcnt lgkmcnt(" #n ")" ::: "memory")
; #define PG8_BAR __builtin_amdgcn_s_barrier()
; #define PG8_SCHED __builtin_amdgcn_sched_barrier(0)
; template <class Epi, bool ALIGN_EPI = false, bool SP2 = true>
; __device__ __forceinline__ void gemm_phase(LAS unsigned char* lds, const Gemm g, const StaticOrder& S, const Epi& E) {
;     ...
;         for (int t = 0; t < nt; t += 2) {
;             const bool last = (t == nt - 2);
;             const char* a1 = cA + (size_t)(t + 1) * kstep;
;             const char* a2 = last ? nA : cA + (size_t)(t + 2) * kstep; const char* b2 = last ? nB : cB + (size_t)(t + 2) * kstep;
;     ...
;             PG8_LDA(At, 1, 1); PG8_STAGE(PG8_SB(1, 0), b3, voffB); PG8_STAGE(PG8_SB(1, 1), b3 + hstep, voffB); PG8_STAGE(PG8_SA(1, 0), a3, voffA);
;             PG8_WAIT_V(8); PG8_WAIT_L(0); PG8_BAR; PG8_MMA(1, 0, At, B0); PG8_MMA(1, 1, At, B1); PG8_BAR; PG8_SCHED;
	s_add_i32 s62, s83, s64
	v_lshl_add_u64 v[160:161], v[160:161], 0, s[24:25]
	s_mov_b32 m0, s62
	ds_read_b128 v[190:193], v168 offset:49152
	ds_read_b128 v[194:197], v168 offset:50176
	ds_read_b128 v[198:201], v168 offset:51200
	ds_read_b128 v[202:205], v168 offset:52224
	ds_read_b128 v[206:209], v168 offset:53248
	ds_read_b128 v[210:213], v168 offset:54272
	ds_read_b128 v[216:219], v168 offset:55296
	ds_read_b128 v[220:223], v168 offset:56320
	global_load_lds_dwordx4 v[160:161], off
	s_add_i32 m0, s62, 0x2000
	s_add_u32 s60, s60, 0x80080
	v_lshl_add_u64 v[160:161], v[224:225], 0, s[24:25]
	s_addc_u32 s61, s61, 0
	s_add_i32 s62, s84, s64
	global_load_lds_dwordx4 v[160:161], off
	v_lshl_add_u64 v[160:161], s[60:61], 0, v[130:131]
	s_mov_b32 m0, s62
	s_nop 0
	global_load_lds_dwordx4 v[160:161], off
	v_lshl_add_u64 v[160:161], s[60:61], 0, v[134:135]
	s_add_i32 m0, s62, 0x2000
	s_nop 0
	global_load_lds_dwordx4 v[160:161], off
	v_lshl_add_u64 v[160:161], v[226:227], 0, s[24:25]
	s_mov_b32 m0, s70
	s_nop 0
	global_load_lds_dwordx4 v[160:161], off
	v_lshl_add_u64 v[160:161], v[228:229], 0, s[24:25]
	s_mov_b32 m0, s71
	s_nop 0
	global_load_lds_dwordx4 v[160:161], off
	s_waitcnt vmcnt(8)
	s_waitcnt lgkmcnt(0)
	s_barrier
	s_waitcnt lgkmcnt(0)
	v_mfma_f32_16x16x32_bf16 v[108:111], v[148:151], v[190:193], v[108:111]
	v_mfma_f32_16x16x32_bf16 v[76:79], v[156:159], v[190:193], v[76:79]
	v_mfma_f32_16x16x32_bf16 v[104:107], v[148:151], v[198:201], v[104:107]
	v_mfma_f32_16x16x32_bf16 v[72:75], v[156:159], v[198:201], v[72:75]
	v_mfma_f32_16x16x32_bf16 v[100:103], v[148:151], v[206:209], v[100:103]
	v_mfma_f32_16x16x32_bf16 v[68:71], v[156:159], v[206:209], v[68:71]
	v_mfma_f32_16x16x32_bf16 v[96:99], v[148:151], v[216:219], v[96:99]
	v_mfma_f32_16x16x32_bf16 v[64:67], v[156:159], v[216:219], v[64:67]
	v_mfma_f32_16x16x32_bf16 v[108:111], v[152:155], v[194:197], v[108:111]
	v_mfma_f32_16x16x32_bf16 v[76:79], v[170:173], v[194:197], v[76:79]
	v_mfma_f32_16x16x32_bf16 v[104:107], v[152:155], v[202:205], v[104:107]
	v_mfma_f32_16x16x32_bf16 v[72:75], v[170:173], v[202:205], v[72:75]
	v_mfma_f32_16x16x32_bf16 v[100:103], v[152:155], v[210:213], v[100:103]
	v_mfma_f32_16x16x32_bf16 v[68:71], v[170:173], v[210:213], v[68:71]
	v_mfma_f32_16x16x32_bf16 v[96:99], v[152:155], v[220:223], v[96:99]
	v_mfma_f32_16x16x32_bf16 v[64:67], v[170:173], v[220:223], v[64:67]
	v_mfma_f32_16x16x32_bf16 v[44:47], v[174:177], v[190:193], v[44:47]
	v_mfma_f32_16x16x32_bf16 v[12:15], v[182:185], v[190:193], v[12:15]
	v_mfma_f32_16x16x32_bf16 v[40:43], v[174:177], v[198:201], v[40:43]
	v_mfma_f32_16x16x32_bf16 v[8:11], v[182:185], v[198:201], v[8:11]
	v_mfma_f32_16x16x32_bf16 v[36:39], v[174:177], v[206:209], v[36:39]
	v_mfma_f32_16x16x32_bf16 v[4:7], v[182:185], v[206:209], v[4:7]
	v_mfma_f32_16x16x32_bf16 v[32:35], v[174:177], v[216:219], v[32:35]
	v_mfma_f32_16x16x32_bf16 v[0:3], v[182:185], v[216:219], v[0:3]
	v_mfma_f32_16x16x32_bf16 v[44:47], v[178:181], v[194:197], v[44:47]
	v_mfma_f32_16x16x32_bf16 v[12:15], v[186:189], v[194:197], v[12:15]
	v_mfma_f32_16x16x32_bf16 v[40:43], v[178:181], v[202:205], v[40:43]
	v_mfma_f32_16x16x32_bf16 v[8:11], v[186:189], v[202:205], v[8:11]
	v_mfma_f32_16x16x32_bf16 v[36:39], v[178:181], v[210:213], v[36:39]
	v_mfma_f32_16x16x32_bf16 v[4:7], v[186:189], v[210:213], v[4:7]
	v_mfma_f32_16x16x32_bf16 v[32:35], v[178:181], v[220:223], v[32:35]
	v_mfma_f32_16x16x32_bf16 v[0:3], v[186:189], v[220:223], v[0:3]
	s_add_i32 s82, s82, 2
	s_add_u32 s10, s10, 0x100
	s_addc_u32 s11, s11, 0
	s_add_u32 s80, s80, 0x100
	s_addc_u32 s81, s81, 0
	s_cmp_gt_u32 s82, 29
	s_barrier
	s_cbranch_scc0 .LBB0_518
	s_and_b64 vcc, exec, s[26:27]
	s_cbranch_vccz .LBB0_521
	s_barrier

; #define PG8_STAGE(bufoff, gbase, voff) do { _Pragma("unroll") for (int _i = 0; _i < 2; ++_i) \
;         __builtin_amdgcn_global_load_lds((const unsigned*)((const char*)(gbase) + (voff)[_i]), (LAS unsigned*)(lds + (bufoff) + ldsw + _i * 8192), 16, 0, 0); } while (0)
; #define PG8_LDA(dst, b, h) do { _Pragma("unroll") for (int m = 0; m < 4; ++m) _Pragma("unroll") for (int k = 0; k < 2; ++k) dst[m][k] = *(const LAS bf16x8*)(lds + PG8_SA(b, h) + aoff + m * 2048 + k * 1024); } while (0)
; #define PG8_LDB(dst, b, h) do { _Pragma("unroll") for (int n = 0; n < 2; ++n) _Pragma("unroll") for (int k = 0; k < 2; ++k) dst[n][k] = *(const LAS bf16x8*)(lds + PG8_SB(b, h) + boff + n * 2048 + k * 1024); } while (0)
; #define PG8_MMA(ai, bj, At, Bt) do { __builtin_amdgcn_s_setprio(1); _Pragma("unroll") for (int m = 0; m < 4; ++m) _Pragma("unroll") for (int n = 0; n < 2; ++n) _Pragma("unroll") for (int k = 0; k < 2; ++k) \
;         acc[ai][bj][m][n] = __builtin_amdgcn_mfma_f32_16x16x32_bf16(Bt[n][k], At[m][k], acc[ai][bj][m][n], 0, 0, 0); __builtin_amdgcn_s_setprio(0); } while (0)
; #define PG8_WAIT_V(n) asm volatile("s_waitcnt vmcnt(" #n ")" ::: "memory")
; #define PG8_WAIT_L(n) asm volatile("s_waitcnt lgkmcnt(" #n ")" ::: "memory")
; #define PG8_BAR __builtin_amdgcn_s_barrier()
; #define PG8_SCHED __builtin_amdgcn_sched_barrier(0)
; template <class Epi, bool ALIGN_EPI = false, bool SP2 = true>
; __device__ __forceinline__ void gemm_phase(LAS unsigned char* lds, const Gemm g, const StaticOrder& S, const Epi& E) {
;     ...
;             PG8_LDB(B0, 0, 0); PG8_LDB(B1, 0, 1); PG8_SCHED; PG8_LDA(At, 0, 0); PG8_STAGE(PG8_SA(1, 1), a1 + hstep, voffA);
;             PG8_WAIT_V(8); PG8_WAIT_L(0); PG8_BAR; PG8_MMA(0, 0, At, B0); PG8_MMA(0, 1, At, B1); PG8_BAR; PG8_SCHED;
;             PG8_LDA(At, 0, 1); PG8_STAGE(PG8_SB(0, 0), b2, voffB); PG8_STAGE(PG8_SB(0, 1), b2 + hstep, voffB); PG8_STAGE(PG8_SA(0, 0), a2, voffA);
;             PG8_WAIT_V(8); PG8_WAIT_L(0); PG8_BAR; PG8_MMA(1, 0, At, B0); PG8_MMA(1, 1, At, B1); PG8_BAR; PG8_SCHED;
.LBB0_746:
	v_add_u32_e32 v161, s66, v150
	s_waitcnt lgkmcnt(0)
	ds_read_b128 v[152:155], v161
	ds_read_b128 v[156:159], v161 offset:1024
	ds_read_b128 v[166:169], v161 offset:2048
	ds_read_b128 v[170:173], v161 offset:3072
	v_add_u32_e32 v161, s67, v150
	s_add_u32 s44, s0, s36
	ds_read_b128 v[174:177], v161
	ds_read_b128 v[178:181], v161 offset:1024
	ds_read_b128 v[182:185], v161 offset:2048
	ds_read_b128 v[186:189], v161 offset:3072
	s_addc_u32 s45, s1, s37
	s_add_u32 s44, s44, 0x100
	s_addc_u32 s45, s45, 0
	s_add_u32 s74, s69, s36
	s_addc_u32 s75, s70, s37
	s_cmpk_eq_i32 s36, 0xf00
	s_cselect_b32 s51, s27, s45
	s_cselect_b32 s50, s71, s44
	s_cselect_b32 s45, s19, s75
	s_cselect_b32 s44, s72, s74
	v_lshl_add_u64 v[162:163], v[144:145], 0, s[36:37]
	s_add_i32 m0, s58, 0xc000
	ds_read_b128 v[190:193], v151
	ds_read_b128 v[194:197], v151 offset:1024
	ds_read_b128 v[198:201], v151 offset:2048
	ds_read_b128 v[202:205], v151 offset:3072
	ds_read_b128 v[206:209], v151 offset:4096
	ds_read_b128 v[210:213], v151 offset:5120
	ds_read_b128 v[214:217], v151 offset:6144
	ds_read_b128 v[218:221], v151 offset:7168
	global_load_lds_dwordx4 v[162:163], off
	v_lshl_add_u64 v[162:163], v[146:147], 0, s[36:37]
	s_add_i32 m0, s58, 0xe000
	s_nop 0
	global_load_lds_dwordx4 v[162:163], off
	s_waitcnt vmcnt(8)
	s_waitcnt lgkmcnt(0)
	s_barrier
	s_waitcnt lgkmcnt(0)
	v_mfma_f32_16x16x32_bf16 v[124:127], v[152:155], v[190:193], v[124:127]
	v_mfma_f32_16x16x32_bf16 v[120:123], v[166:169], v[190:193], v[120:123]
	v_mfma_f32_16x16x32_bf16 v[108:111], v[152:155], v[198:201], v[108:111]
	v_mfma_f32_16x16x32_bf16 v[104:107], v[166:169], v[198:201], v[104:107]
	v_mfma_f32_16x16x32_bf16 v[92:95], v[152:155], v[206:209], v[92:95]
	v_mfma_f32_16x16x32_bf16 v[88:91], v[166:169], v[206:209], v[88:91]
	v_mfma_f32_16x16x32_bf16 v[76:79], v[152:155], v[214:217], v[76:79]
	v_mfma_f32_16x16x32_bf16 v[72:75], v[166:169], v[214:217], v[72:75]
	v_mfma_f32_16x16x32_bf16 v[124:127], v[156:159], v[194:197], v[124:127]
	v_mfma_f32_16x16x32_bf16 v[120:123], v[170:173], v[194:197], v[120:123]
	v_mfma_f32_16x16x32_bf16 v[108:111], v[156:159], v[202:205], v[108:111]
	v_mfma_f32_16x16x32_bf16 v[104:107], v[170:173], v[202:205], v[104:107]
	v_mfma_f32_16x16x32_bf16 v[92:95], v[156:159], v[210:213], v[92:95]
	v_mfma_f32_16x16x32_bf16 v[88:91], v[170:173], v[210:213], v[88:91]
	v_mfma_f32_16x16x32_bf16 v[76:79], v[156:159], v[218:221], v[76:79]
	v_mfma_f32_16x16x32_bf16 v[72:75], v[170:173], v[218:221], v[72:75]
	v_mfma_f32_16x16x32_bf16 v[116:119], v[174:177], v[190:193], v[116:119]
	v_mfma_f32_16x16x32_bf16 v[112:115], v[182:185], v[190:193], v[112:115]
	v_mfma_f32_16x16x32_bf16 v[100:103], v[174:177], v[198:201], v[100:103]
	v_mfma_f32_16x16x32_bf16 v[96:99], v[182:185], v[198:201], v[96:99]
	v_mfma_f32_16x16x32_bf16 v[84:87], v[174:177], v[206:209], v[84:87]
	v_mfma_f32_16x16x32_bf16 v[80:83], v[182:185], v[206:209], v[80:83]
	v_mfma_f32_16x16x32_bf16 v[68:71], v[174:177], v[214:217], v[68:71]
	v_mfma_f32_16x16x32_bf16 v[64:67], v[182:185], v[214:217], v[64:67]
	v_mfma_f32_16x16x32_bf16 v[116:119], v[178:181], v[194:197], v[116:119]
	v_mfma_f32_16x16x32_bf16 v[112:115], v[186:189], v[194:197], v[112:115]
	v_mfma_f32_16x16x32_bf16 v[100:103], v[178:181], v[202:205], v[100:103]
	v_mfma_f32_16x16x32_bf16 v[96:99], v[186:189], v[202:205], v[96:99]
	v_mfma_f32_16x16x32_bf16 v[84:87], v[178:181], v[210:213], v[84:87]
	v_mfma_f32_16x16x32_bf16 v[80:83], v[186:189], v[210:213], v[80:83]
	v_mfma_f32_16x16x32_bf16 v[68:71], v[178:181], v[218:221], v[68:71]
	v_mfma_f32_16x16x32_bf16 v[64:67], v[186:189], v[218:221], v[64:67]
	s_barrier
	s_add_i32 s74, s66, s57
	v_lshl_add_u64 v[162:163], s[44:45], 0, v[130:131]
	s_mov_b32 m0, s74
	ds_read_b128 v[190:193], v151 offset:16384
	ds_read_b128 v[194:197], v151 offset:17408
	ds_read_b128 v[198:201], v151 offset:18432
	ds_read_b128 v[202:205], v151 offset:19456
	ds_read_b128 v[206:209], v151 offset:20480
	ds_read_b128 v[210:213], v151 offset:21504
	ds_read_b128 v[214:217], v151 offset:22528
	ds_read_b128 v[218:221], v151 offset:23552
	global_load_lds_dwordx4 v[162:163], off
	s_add_i32 m0, s74, 0x2000
	s_add_u32 s74, s44, 0x80000
	v_lshl_add_u64 v[222:223], s[44:45], 0, v[134:135]
	s_addc_u32 s75, s45, 0
	s_add_i32 s76, s67, s57
	global_load_lds_dwordx4 v[222:223], off
	v_lshl_add_u64 v[224:225], s[74:75], 0, v[130:131]
	s_mov_b32 m0, s76
	v_lshl_add_u64 v[226:227], s[50:51], 0, v[132:133]
	global_load_lds_dwordx4 v[224:225], off
	v_lshl_add_u64 v[224:225], s[74:75], 0, v[134:135]
	s_add_i32 m0, s76, 0x2000
	s_nop 0
	global_load_lds_dwordx4 v[224:225], off
	v_lshl_add_u64 v[224:225], s[50:51], 0, v[128:129]
	s_mov_b32 m0, s58
	s_nop 0
	global_load_lds_dwordx4 v[224:225], off
	s_mov_b32 m0, s59
	s_nop 0
	global_load_lds_dwordx4 v[226:227], off
	s_waitcnt vmcnt(8)
	s_waitcnt lgkmcnt(0)
	s_barrier
; #define PG8_STAGE(bufoff, gbase, voff) do { _Pragma("unroll") for (int _i = 0; _i < 2; ++_i) \
;         __builtin_amdgcn_global_load_lds((const unsigned*)((const char*)(gbase) + (voff)[_i]), (LAS unsigned*)(lds + (bufoff) + ldsw + _i * 8192), 16, 0, 0); } while (0)
; #define PG8_LDA(dst, b, h) do { _Pragma("unroll") for (int m = 0; m < 4; ++m) _Pragma("unroll") for (int k = 0; k < 2; ++k) dst[m][k] = *(const LAS bf16x8*)(lds + PG8_SA(b, h) + aoff + m * 2048 + k * 1024); } while (0)
; #define PG8_LDB(dst, b, h) do { _Pragma("unroll") for (int n = 0; n < 2; ++n) _Pragma("unroll") for (int k = 0; k < 2; ++k) dst[n][k] = *(const LAS bf16x8*)(lds + PG8_SB(b, h) + boff + n * 2048 + k * 1024); } while (0)
; #define PG8_MMA(ai, bj, At, Bt) do { __builtin_amdgcn_s_setprio(1); _Pragma("unroll") for (int m = 0; m < 4; ++m) _Pragma("unroll") for (int n = 0; n < 2; ++n) _Pragma("unroll") for (int k = 0; k < 2; ++k) \
;         acc[ai][bj][m][n] = __builtin_amdgcn_mfma_f32_16x16x32_bf16(Bt[n][k], At[m][k], acc[ai][bj][m][n], 0, 0, 0); __builtin_amdgcn_s_setprio(0); } while (0)
; #define PG8_WAIT_V(n) asm volatile("s_waitcnt vmcnt(" #n ")" ::: "memory")
; #define PG8_WAIT_L(n) asm volatile("s_waitcnt lgkmcnt(" #n ")" ::: "memory")
; #define PG8_BAR __builtin_amdgcn_s_barrier()
; #define PG8_SCHED __builtin_amdgcn_sched_barrier(0)
; template <class Epi, bool ALIGN_EPI = false, bool SP2 = true>
; __device__ __forceinline__ void gemm_phase(LAS unsigned char* lds, const Gemm g, const StaticOrder& S, const Epi& E) {
;     ...
;             PG8_WAIT_V(8); PG8_WAIT_L(0); PG8_BAR; PG8_MMA(1, 0, At, B0); PG8_MMA(1, 1, At, B1); PG8_BAR; PG8_SCHED;
;             PG8_LDB(B0, 1, 0); PG8_LDB(B1, 1, 1); PG8_SCHED; PG8_LDA(At, 1, 0); PG8_STAGE(PG8_SA(0, 1), a2 + hstep, voffA);
;             PG8_WAIT_V(8); PG8_WAIT_L(0); PG8_BAR; PG8_MMA(0, 0, At, B0); PG8_MMA(0, 1, At, B1); PG8_BAR; PG8_SCHED;
	s_waitcnt lgkmcnt(0)
	v_mfma_f32_16x16x32_bf16 v[60:63], v[152:155], v[190:193], v[60:63]
	v_mfma_f32_16x16x32_bf16 v[56:59], v[166:169], v[190:193], v[56:59]
	v_mfma_f32_16x16x32_bf16 v[44:47], v[152:155], v[198:201], v[44:47]
	v_mfma_f32_16x16x32_bf16 v[40:43], v[166:169], v[198:201], v[40:43]
	v_mfma_f32_16x16x32_bf16 v[28:31], v[152:155], v[206:209], v[28:31]
	v_mfma_f32_16x16x32_bf16 v[24:27], v[166:169], v[206:209], v[24:27]
	v_mfma_f32_16x16x32_bf16 v[12:15], v[152:155], v[214:217], v[12:15]
	v_mfma_f32_16x16x32_bf16 v[8:11], v[166:169], v[214:217], v[8:11]
	v_mfma_f32_16x16x32_bf16 v[60:63], v[156:159], v[194:197], v[60:63]
	v_mfma_f32_16x16x32_bf16 v[56:59], v[170:173], v[194:197], v[56:59]
	v_mfma_f32_16x16x32_bf16 v[44:47], v[156:159], v[202:205], v[44:47]
	v_mfma_f32_16x16x32_bf16 v[40:43], v[170:173], v[202:205], v[40:43]
	v_mfma_f32_16x16x32_bf16 v[28:31], v[156:159], v[210:213], v[28:31]
	v_mfma_f32_16x16x32_bf16 v[24:27], v[170:173], v[210:213], v[24:27]
	v_mfma_f32_16x16x32_bf16 v[12:15], v[156:159], v[218:221], v[12:15]
	v_mfma_f32_16x16x32_bf16 v[8:11], v[170:173], v[218:221], v[8:11]
	v_mfma_f32_16x16x32_bf16 v[52:55], v[174:177], v[190:193], v[52:55]
	v_mfma_f32_16x16x32_bf16 v[48:51], v[182:185], v[190:193], v[48:51]
	v_mfma_f32_16x16x32_bf16 v[36:39], v[174:177], v[198:201], v[36:39]
	v_mfma_f32_16x16x32_bf16 v[32:35], v[182:185], v[198:201], v[32:35]
	v_mfma_f32_16x16x32_bf16 v[20:23], v[174:177], v[206:209], v[20:23]
	v_mfma_f32_16x16x32_bf16 v[16:19], v[182:185], v[206:209], v[16:19]
	v_mfma_f32_16x16x32_bf16 v[4:7], v[174:177], v[214:217], v[4:7]
	v_mfma_f32_16x16x32_bf16 v[0:3], v[182:185], v[214:217], v[0:3]
	v_mfma_f32_16x16x32_bf16 v[52:55], v[178:181], v[194:197], v[52:55]
	v_mfma_f32_16x16x32_bf16 v[48:51], v[186:189], v[194:197], v[48:51]
	v_mfma_f32_16x16x32_bf16 v[36:39], v[178:181], v[202:205], v[36:39]
	v_mfma_f32_16x16x32_bf16 v[32:35], v[186:189], v[202:205], v[32:35]
	v_mfma_f32_16x16x32_bf16 v[20:23], v[178:181], v[210:213], v[20:23]
	v_mfma_f32_16x16x32_bf16 v[16:19], v[186:189], v[210:213], v[16:19]
	v_mfma_f32_16x16x32_bf16 v[4:7], v[178:181], v[218:221], v[4:7]
	v_mfma_f32_16x16x32_bf16 v[0:3], v[186:189], v[218:221], v[0:3]
	s_barrier
	s_add_i32 s74, 0, 0x18000
	v_add_u32_e32 v161, s74, v150
	s_add_i32 s75, 0, 0x1c000
	ds_read_b128 v[152:155], v161
	ds_read_b128 v[156:159], v161 offset:1024
	ds_read_b128 v[166:169], v161 offset:2048
	ds_read_b128 v[170:173], v161 offset:3072
	v_add_u32_e32 v161, s75, v150
	ds_read_b128 v[174:177], v161
	ds_read_b128 v[178:181], v161 offset:1024
	ds_read_b128 v[182:185], v161 offset:2048
	ds_read_b128 v[186:189], v161 offset:3072
	s_add_u32 s50, s50, 0x80000
	s_addc_u32 s51, s51, 0
	s_mov_b32 m0, s60
	v_lshl_add_u64 v[228:229], s[50:51], 0, v[128:129]
	ds_read_b128 v[190:193], v151 offset:32768
	ds_read_b128 v[194:197], v151 offset:33792
	ds_read_b128 v[198:201], v151 offset:34816
	ds_read_b128 v[202:205], v151 offset:35840
	ds_read_b128 v[206:209], v151 offset:36864
	ds_read_b128 v[210:213], v151 offset:37888
	ds_read_b128 v[214:217], v151 offset:38912
	ds_read_b128 v[218:221], v151 offset:39936
	global_load_lds_dwordx4 v[228:229], off
	v_lshl_add_u64 v[228:229], s[50:51], 0, v[132:133]
	s_mov_b32 m0, s61
	s_nop 0
	global_load_lds_dwordx4 v[228:229], off
	s_waitcnt vmcnt(8)
	s_waitcnt lgkmcnt(0)
	s_barrier
	s_waitcnt lgkmcnt(0)
	v_mfma_f32_16x16x32_bf16 v[124:127], v[152:155], v[190:193], v[124:127]
	v_mfma_f32_16x16x32_bf16 v[120:123], v[166:169], v[190:193], v[120:123]
	v_mfma_f32_16x16x32_bf16 v[108:111], v[152:155], v[198:201], v[108:111]
	v_mfma_f32_16x16x32_bf16 v[104:107], v[166:169], v[198:201], v[104:107]
	v_mfma_f32_16x16x32_bf16 v[92:95], v[152:155], v[206:209], v[92:95]
	v_mfma_f32_16x16x32_bf16 v[88:91], v[166:169], v[206:209], v[88:91]
	v_mfma_f32_16x16x32_bf16 v[76:79], v[152:155], v[214:217], v[76:79]
	v_mfma_f32_16x16x32_bf16 v[72:75], v[166:169], v[214:217], v[72:75]
	v_mfma_f32_16x16x32_bf16 v[124:127], v[156:159], v[194:197], v[124:127]
	v_mfma_f32_16x16x32_bf16 v[120:123], v[170:173], v[194:197], v[120:123]
	v_mfma_f32_16x16x32_bf16 v[108:111], v[156:159], v[202:205], v[108:111]
	v_mfma_f32_16x16x32_bf16 v[104:107], v[170:173], v[202:205], v[104:107]
	v_mfma_f32_16x16x32_bf16 v[92:95], v[156:159], v[210:213], v[92:95]
	v_mfma_f32_16x16x32_bf16 v[88:91], v[170:173], v[210:213], v[88:91]
	v_mfma_f32_16x16x32_bf16 v[76:79], v[156:159], v[218:221], v[76:79]
	v_mfma_f32_16x16x32_bf16 v[72:75], v[170:173], v[218:221], v[72:75]
	v_mfma_f32_16x16x32_bf16 v[116:119], v[174:177], v[190:193], v[116:119]
	v_mfma_f32_16x16x32_bf16 v[112:115], v[182:185], v[190:193], v[112:115]
	v_mfma_f32_16x16x32_bf16 v[100:103], v[174:177], v[198:201], v[100:103]
	v_mfma_f32_16x16x32_bf16 v[96:99], v[182:185], v[198:201], v[96:99]
	v_mfma_f32_16x16x32_bf16 v[84:87], v[174:177], v[206:209], v[84:87]
	v_mfma_f32_16x16x32_bf16 v[80:83], v[182:185], v[206:209], v[80:83]
	v_mfma_f32_16x16x32_bf16 v[68:71], v[174:177], v[214:217], v[68:71]
	v_mfma_f32_16x16x32_bf16 v[64:67], v[182:185], v[214:217], v[64:67]
	v_mfma_f32_16x16x32_bf16 v[116:119], v[178:181], v[194:197], v[116:119]
	v_mfma_f32_16x16x32_bf16 v[112:115], v[186:189], v[194:197], v[112:115]
	v_mfma_f32_16x16x32_bf16 v[100:103], v[178:181], v[202:205], v[100:103]
	v_mfma_f32_16x16x32_bf16 v[96:99], v[186:189], v[202:205], v[96:99]
	v_mfma_f32_16x16x32_bf16 v[84:87], v[178:181], v[210:213], v[84:87]
	v_mfma_f32_16x16x32_bf16 v[80:83], v[186:189], v[210:213], v[80:83]
	v_mfma_f32_16x16x32_bf16 v[68:71], v[178:181], v[218:221], v[68:71]
	v_mfma_f32_16x16x32_bf16 v[64:67], v[186:189], v[218:221], v[64:67]
	s_barrier
; #define PG8_STAGE(bufoff, gbase, voff) do { _Pragma("unroll") for (int _i = 0; _i < 2; ++_i) \
;         __builtin_amdgcn_global_load_lds((const unsigned*)((const char*)(gbase) + (voff)[_i]), (LAS unsigned*)(lds + (bufoff) + ldsw + _i * 8192), 16, 0, 0); } while (0)
; #define PG8_LDA(dst, b, h) do { _Pragma("unroll") for (int m = 0; m < 4; ++m) _Pragma("unroll") for (int k = 0; k < 2; ++k) dst[m][k] = *(const LAS bf16x8*)(lds + PG8_SA(b, h) + aoff + m * 2048 + k * 1024); } while (0)
; #define PG8_MMA(ai, bj, At, Bt) do { __builtin_amdgcn_s_setprio(1); _Pragma("unroll") for (int m = 0; m < 4; ++m) _Pragma("unroll") for (int n = 0; n < 2; ++n) _Pragma("unroll") for (int k = 0; k < 2; ++k) \
;         acc[ai][bj][m][n] = __builtin_amdgcn_mfma_f32_16x16x32_bf16(Bt[n][k], At[m][k], acc[ai][bj][m][n], 0, 0, 0); __builtin_amdgcn_s_setprio(0); } while (0)
; #define PG8_WAIT_V(n) asm volatile("s_waitcnt vmcnt(" #n ")" ::: "memory")
; #define PG8_WAIT_L(n) asm volatile("s_waitcnt lgkmcnt(" #n ")" ::: "memory")
; #define PG8_BAR __builtin_amdgcn_s_barrier()
; #define PG8_SCHED __builtin_amdgcn_sched_barrier(0)
; template <class Epi, bool ALIGN_EPI = false, bool SP2 = true>
; __device__ __forceinline__ void gemm_phase(LAS unsigned char* lds, const Gemm g, const StaticOrder& S, const Epi& E) {
;     ...
;             PG8_LDA(At, 1, 1); PG8_STAGE(PG8_SB(1, 0), b3, voffB); PG8_STAGE(PG8_SB(1, 1), b3 + hstep, voffB); PG8_STAGE(PG8_SA(1, 0), a3, voffA);
;             PG8_WAIT_V(8); PG8_WAIT_L(0); PG8_BAR; PG8_MMA(1, 0, At, B0); PG8_MMA(1, 1, At, B1); PG8_BAR; PG8_SCHED;
;     ...
; #pragma unroll
;         for (int a = 0; a < 2; ++a)
; #pragma unroll
;             for (int b = 0; b < 2; ++b)
; #pragma unroll
;                 for (int m = 0; m < 4; ++m)
; #pragma unroll
;                     for (int n = 0; n < 2; ++n) acc[a][b][m][n] = (f32x4){0.f, 0.f, 0.f, 0.f};
;         cur = nxt; cA = nA; cB = nB; ++ui;
	s_add_i32 s50, s74, s57
	v_lshl_add_u64 v[162:163], v[162:163], 0, s[16:17]
	s_mov_b32 m0, s50
	ds_read_b128 v[190:193], v151 offset:49152
	ds_read_b128 v[194:197], v151 offset:50176
	ds_read_b128 v[198:201], v151 offset:51200
	ds_read_b128 v[202:205], v151 offset:52224
	ds_read_b128 v[206:209], v151 offset:53248
	ds_read_b128 v[210:213], v151 offset:54272
	ds_read_b128 v[214:217], v151 offset:55296
	ds_read_b128 v[218:221], v151 offset:56320
	global_load_lds_dwordx4 v[162:163], off
	s_add_i32 m0, s50, 0x2000
	s_add_u32 s44, s44, 0x80080
	v_lshl_add_u64 v[162:163], v[222:223], 0, s[16:17]
	s_addc_u32 s45, s45, 0
	s_add_i32 s50, s75, s57
	global_load_lds_dwordx4 v[162:163], off
	v_lshl_add_u64 v[162:163], s[44:45], 0, v[130:131]
	s_mov_b32 m0, s50
	s_nop 0
	global_load_lds_dwordx4 v[162:163], off
	v_lshl_add_u64 v[162:163], s[44:45], 0, v[134:135]
	s_add_i32 m0, s50, 0x2000
	s_nop 0
	global_load_lds_dwordx4 v[162:163], off
	v_lshl_add_u64 v[162:163], v[224:225], 0, s[16:17]
	s_mov_b32 m0, s63
	s_nop 0
	global_load_lds_dwordx4 v[162:163], off
	v_lshl_add_u64 v[162:163], v[226:227], 0, s[16:17]
	s_mov_b32 m0, s64
	s_nop 0
	global_load_lds_dwordx4 v[162:163], off
	s_waitcnt vmcnt(8)
	s_waitcnt lgkmcnt(0)
	s_barrier
	s_waitcnt lgkmcnt(0)
	v_mfma_f32_16x16x32_bf16 v[60:63], v[152:155], v[190:193], v[60:63]
	v_mfma_f32_16x16x32_bf16 v[56:59], v[166:169], v[190:193], v[56:59]
	v_mfma_f32_16x16x32_bf16 v[44:47], v[152:155], v[198:201], v[44:47]
	v_mfma_f32_16x16x32_bf16 v[40:43], v[166:169], v[198:201], v[40:43]
	v_mfma_f32_16x16x32_bf16 v[28:31], v[152:155], v[206:209], v[28:31]
	v_mfma_f32_16x16x32_bf16 v[24:27], v[166:169], v[206:209], v[24:27]
	v_mfma_f32_16x16x32_bf16 v[12:15], v[152:155], v[214:217], v[12:15]
	v_mfma_f32_16x16x32_bf16 v[8:11], v[166:169], v[214:217], v[8:11]
	v_mfma_f32_16x16x32_bf16 v[60:63], v[156:159], v[194:197], v[60:63]
	v_mfma_f32_16x16x32_bf16 v[56:59], v[170:173], v[194:197], v[56:59]
	v_mfma_f32_16x16x32_bf16 v[44:47], v[156:159], v[202:205], v[44:47]
	v_mfma_f32_16x16x32_bf16 v[40:43], v[170:173], v[202:205], v[40:43]
	v_mfma_f32_16x16x32_bf16 v[28:31], v[156:159], v[210:213], v[28:31]
	v_mfma_f32_16x16x32_bf16 v[24:27], v[170:173], v[210:213], v[24:27]
	v_mfma_f32_16x16x32_bf16 v[12:15], v[156:159], v[218:221], v[12:15]
	v_mfma_f32_16x16x32_bf16 v[8:11], v[170:173], v[218:221], v[8:11]
	v_mfma_f32_16x16x32_bf16 v[52:55], v[174:177], v[190:193], v[52:55]
	v_mfma_f32_16x16x32_bf16 v[48:51], v[182:185], v[190:193], v[48:51]
	v_mfma_f32_16x16x32_bf16 v[36:39], v[174:177], v[198:201], v[36:39]
	v_mfma_f32_16x16x32_bf16 v[32:35], v[182:185], v[198:201], v[32:35]
	v_mfma_f32_16x16x32_bf16 v[20:23], v[174:177], v[206:209], v[20:23]
	v_mfma_f32_16x16x32_bf16 v[16:19], v[182:185], v[206:209], v[16:19]
	v_mfma_f32_16x16x32_bf16 v[4:7], v[174:177], v[214:217], v[4:7]
	v_mfma_f32_16x16x32_bf16 v[0:3], v[182:185], v[214:217], v[0:3]
	v_mfma_f32_16x16x32_bf16 v[52:55], v[178:181], v[194:197], v[52:55]
	v_mfma_f32_16x16x32_bf16 v[48:51], v[186:189], v[194:197], v[48:51]
	v_mfma_f32_16x16x32_bf16 v[36:39], v[178:181], v[202:205], v[36:39]
	v_mfma_f32_16x16x32_bf16 v[32:35], v[186:189], v[202:205], v[32:35]
	v_mfma_f32_16x16x32_bf16 v[20:23], v[178:181], v[210:213], v[20:23]
	v_mfma_f32_16x16x32_bf16 v[16:19], v[186:189], v[210:213], v[16:19]
	v_mfma_f32_16x16x32_bf16 v[4:7], v[178:181], v[218:221], v[4:7]
	v_mfma_f32_16x16x32_bf16 v[0:3], v[186:189], v[218:221], v[0:3]
	s_add_i32 s73, s73, 2
	s_add_u32 s36, s36, 0x100
	s_addc_u32 s37, s37, 0
	s_cmp_gt_u32 s73, 29
	s_barrier
	s_cbranch_scc0 .LBB0_746
	s_add_u32 s36, s69, 0xffffff00
	s_addc_u32 s37, s70, -1
	s_andn2_b64 vcc, exec, s[6:7]
	s_cbranch_vccnz .LBB0_749
	v_mov_b32_e32 v0, 0
	s_mov_b32 s14, s18
	s_mov_b32 s10, s26
	s_mov_b64 s[0:1], s[30:31]
	s_mov_b32 s65, s68
	v_mov_b32_e32 v1, v0
	v_mov_b32_e32 v2, v0
	v_mov_b32_e32 v3, v0
	v_mov_b32_e32 v4, v0
	v_mov_b32_e32 v5, v0
	v_mov_b32_e32 v6, v0
	v_mov_b32_e32 v7, v0
	v_mov_b32_e32 v16, v0
	v_mov_b32_e32 v17, v0
	v_mov_b32_e32 v18, v0
	v_mov_b32_e32 v19, v0
	v_mov_b32_e32 v20, v0
	v_mov_b32_e32 v21, v0
	v_mov_b32_e32 v22, v0
	v_mov_b32_e32 v23, v0
	v_mov_b32_e32 v32, v0
	v_mov_b32_e32 v33, v0
	v_mov_b32_e32 v34, v0
	v_mov_b32_e32 v35, v0
	v_mov_b32_e32 v36, v0
	v_mov_b32_e32 v37, v0
	v_mov_b32_e32 v38, v0
	v_mov_b32_e32 v39, v0
	v_mov_b32_e32 v48, v0
	v_mov_b32_e32 v49, v0
	v_mov_b32_e32 v50, v0
	v_mov_b32_e32 v51, v0
	v_mov_b32_e32 v52, v0
	v_mov_b32_e32 v53, v0
	v_mov_b32_e32 v54, v0
	v_mov_b32_e32 v55, v0
	v_mov_b32_e32 v8, v0
	v_mov_b32_e32 v9, v0
	v_mov_b32_e32 v10, v0
	v_mov_b32_e32 v11, v0
	v_mov_b32_e32 v12, v0
	v_mov_b32_e32 v13, v0
	v_mov_b32_e32 v14, v0
	v_mov_b32_e32 v15, v0
	v_mov_b32_e32 v24, v0
	v_mov_b32_e32 v25, v0
	v_mov_b32_e32 v26, v0
	v_mov_b32_e32 v27, v0
	v_mov_b32_e32 v28, v0
	v_mov_b32_e32 v29, v0
	v_mov_b32_e32 v30, v0
	v_mov_b32_e32 v31, v0
	v_mov_b32_e32 v40, v0
	v_mov_b32_e32 v41, v0
	v_mov_b32_e32 v42, v0
	v_mov_b32_e32 v43, v0
	v_mov_b32_e32 v44, v0
	v_mov_b32_e32 v45, v0
	v_mov_b32_e32 v46, v0
	v_mov_b32_e32 v47, v0
	v_mov_b32_e32 v56, v0
	v_mov_b32_e32 v57, v0
	v_mov_b32_e32 v58, v0
	v_mov_b32_e32 v59, v0
	v_mov_b32_e32 v60, v0
	v_mov_b32_e32 v61, v0
	v_mov_b32_e32 v62, v0
	v_mov_b32_e32 v63, v0
	v_mov_b32_e32 v64, v0
	v_mov_b32_e32 v65, v0
	v_mov_b32_e32 v66, v0
	v_mov_b32_e32 v67, v0
	v_mov_b32_e32 v68, v0
	v_mov_b32_e32 v69, v0
	v_mov_b32_e32 v70, v0
	v_mov_b32_e32 v71, v0
	v_mov_b32_e32 v80, v0
	v_mov_b32_e32 v81, v0
	v_mov_b32_e32 v82, v0
	v_mov_b32_e32 v83, v0
	v_mov_b32_e32 v84, v0
	v_mov_b32_e32 v85, v0
	v_mov_b32_e32 v86, v0
	v_mov_b32_e32 v87, v0
	v_mov_b32_e32 v96, v0
	v_mov_b32_e32 v97, v0
	v_mov_b32_e32 v98, v0
	v_mov_b32_e32 v99, v0
	v_mov_b32_e32 v100, v0
	v_mov_b32_e32 v101, v0
	v_mov_b32_e32 v102, v0
	v_mov_b32_e32 v103, v0
	v_mov_b32_e32 v112, v0
	v_mov_b32_e32 v113, v0
	v_mov_b32_e32 v114, v0
	v_mov_b32_e32 v115, v0
	v_mov_b32_e32 v116, v0
	v_mov_b32_e32 v117, v0
	v_mov_b32_e32 v118, v0
	v_mov_b32_e32 v119, v0
	v_mov_b32_e32 v72, v0
	v_mov_b32_e32 v73, v0
	v_mov_b32_e32 v74, v0
	v_mov_b32_e32 v75, v0
	v_mov_b32_e32 v76, v0
	v_mov_b32_e32 v77, v0
	v_mov_b32_e32 v78, v0
	v_mov_b32_e32 v79, v0
	v_mov_b32_e32 v88, v0
	v_mov_b32_e32 v89, v0
	v_mov_b32_e32 v90, v0
	v_mov_b32_e32 v91, v0
	v_mov_b32_e32 v92, v0
	v_mov_b32_e32 v93, v0
	v_mov_b32_e32 v94, v0
	v_mov_b32_e32 v95, v0
	v_mov_b32_e32 v104, v0
	v_mov_b32_e32 v105, v0
	v_mov_b32_e32 v106, v0
	v_mov_b32_e32 v107, v0
	v_mov_b32_e32 v108, v0
	v_mov_b32_e32 v109, v0
	v_mov_b32_e32 v110, v0
	v_mov_b32_e32 v111, v0
	v_mov_b32_e32 v120, v0
	v_mov_b32_e32 v121, v0
	v_mov_b32_e32 v122, v0
	v_mov_b32_e32 v123, v0
	v_mov_b32_e32 v124, v0
	v_mov_b32_e32 v125, v0
	v_mov_b32_e32 v126, v0
	v_mov_b32_e32 v127, v0
	s_andn2_b64 vcc, exec, s[4:5]
	s_cbranch_vccnz .LBB0_750
	s_branch .LBB0_751

; #define PG8_STAGE(bufoff, gbase, voff) do { _Pragma("unroll") for (int _i = 0; _i < 2; ++_i) \
;         __builtin_amdgcn_global_load_lds((const unsigned*)((const char*)(gbase) + (voff)[_i]), (LAS unsigned*)(lds + (bufoff) + ldsw + _i * 8192), 16, 0, 0); } while (0)
; #define PG8_LDA(dst, b, h) do { _Pragma("unroll") for (int m = 0; m < 4; ++m) _Pragma("unroll") for (int k = 0; k < 2; ++k) dst[m][k] = *(const LAS bf16x8*)(lds + PG8_SA(b, h) + aoff + m * 2048 + k * 1024); } while (0)
; #define PG8_LDB(dst, b, h) do { _Pragma("unroll") for (int n = 0; n < 2; ++n) _Pragma("unroll") for (int k = 0; k < 2; ++k) dst[n][k] = *(const LAS bf16x8*)(lds + PG8_SB(b, h) + boff + n * 2048 + k * 1024); } while (0)
; #define PG8_MMA(ai, bj, At, Bt) do { __builtin_amdgcn_s_setprio(1); _Pragma("unroll") for (int m = 0; m < 4; ++m) _Pragma("unroll") for (int n = 0; n < 2; ++n) _Pragma("unroll") for (int k = 0; k < 2; ++k) \
;         acc[ai][bj][m][n] = __builtin_amdgcn_mfma_f32_16x16x32_bf16(Bt[n][k], At[m][k], acc[ai][bj][m][n], 0, 0, 0); __builtin_amdgcn_s_setprio(0); } while (0)
; #define PG8_WAIT_V(n) asm volatile("s_waitcnt vmcnt(" #n ")" ::: "memory")
; #define PG8_WAIT_L(n) asm volatile("s_waitcnt lgkmcnt(" #n ")" ::: "memory")
; #define PG8_BAR __builtin_amdgcn_s_barrier()
; #define PG8_SCHED __builtin_amdgcn_sched_barrier(0)
; template <class Epi, bool ALIGN_EPI = false, bool SP2 = true>
; __device__ __forceinline__ void gemm_phase(LAS unsigned char* lds, const Gemm g, const StaticOrder& S, const Epi& E) {
;     ...
;             const char* a2 = last ? nA : cA + (size_t)(t + 2) * kstep; const char* b2 = last ? nB : cB + (size_t)(t + 2) * kstep;
;             const char* a3 = a2 + kstep; const char* b3 = b2 + kstep;
;             if constexpr (SP2) {
;             PG8_LDB(B0, 0, 0); PG8_LDB(B1, 0, 1); PG8_SCHED; PG8_LDA(At, 0, 0); PG8_STAGE(PG8_SA(1, 1), a1 + hstep, voffA);
;             PG8_WAIT_V(8); PG8_WAIT_L(0); PG8_BAR; PG8_MMA(0, 0, At, B0); PG8_MMA(0, 1, At, B1); PG8_BAR; PG8_SCHED;
;             PG8_LDA(At, 0, 1); PG8_STAGE(PG8_SB(0, 0), b2, voffB); PG8_STAGE(PG8_SB(0, 1), b2 + hstep, voffB); PG8_STAGE(PG8_SA(0, 0), a2, voffA);
;             PG8_WAIT_V(8); PG8_WAIT_L(0); PG8_BAR; PG8_MMA(1, 0, At, B0); PG8_MMA(1, 1, At, B1); PG8_BAR; PG8_SCHED;
.LBB0_855:
	ds_read_b128 v[128:131], v187
	ds_read_b128 v[132:135], v187 offset:1024
	ds_read_b128 v[136:139], v187 offset:2048
	ds_read_b128 v[140:143], v187 offset:3072
	ds_read_b128 v[144:147], v188
	ds_read_b128 v[148:151], v188 offset:1024
	s_waitcnt lgkmcnt(0)
	ds_read_b128 v[152:155], v188 offset:2048
	ds_read_b128 v[156:159], v188 offset:3072
	s_add_u32 s44, s40, 0xfff80080
	s_addc_u32 s45, s41, -1
	s_cmp_eq_u32 s68, 28
	s_cselect_b32 s47, s29, s45
	s_cselect_b32 s46, s64, s44
	s_cselect_b32 s45, s27, s67
	s_cselect_b32 s44, s65, s66
	v_lshl_add_u64 v[214:215], s[40:41], 0, v[164:165]
	s_add_i32 m0, s35, 0xc000
	ds_read_b128 v[160:163], v189
	ds_read_b128 v[180:183], v189 offset:1024
	ds_read_b128 v[190:193], v189 offset:2048
	ds_read_b128 v[194:197], v189 offset:3072
	ds_read_b128 v[198:201], v189 offset:4096
	ds_read_b128 v[202:205], v189 offset:5120
	ds_read_b128 v[206:209], v189 offset:6144
	ds_read_b128 v[210:213], v189 offset:7168
	global_load_lds_dwordx4 v[214:215], off
	v_lshl_add_u64 v[214:215], s[40:41], 0, v[174:175]
	s_add_i32 m0, s35, 0xe000
	s_nop 0
	global_load_lds_dwordx4 v[214:215], off
	s_waitcnt vmcnt(8)
	s_waitcnt lgkmcnt(0)
	s_barrier
	s_waitcnt lgkmcnt(0)
	v_mfma_f32_16x16x32_bf16 v[124:127], v[128:131], v[160:163], v[124:127]
	v_mfma_f32_16x16x32_bf16 v[120:123], v[136:139], v[160:163], v[120:123]
	v_mfma_f32_16x16x32_bf16 v[108:111], v[128:131], v[190:193], v[108:111]
	v_mfma_f32_16x16x32_bf16 v[104:107], v[136:139], v[190:193], v[104:107]
	v_mfma_f32_16x16x32_bf16 v[92:95], v[128:131], v[198:201], v[92:95]
	v_mfma_f32_16x16x32_bf16 v[88:91], v[136:139], v[198:201], v[88:91]
	v_mfma_f32_16x16x32_bf16 v[76:79], v[128:131], v[206:209], v[76:79]
	v_mfma_f32_16x16x32_bf16 v[72:75], v[136:139], v[206:209], v[72:75]
	v_mfma_f32_16x16x32_bf16 v[124:127], v[132:135], v[180:183], v[124:127]
	v_mfma_f32_16x16x32_bf16 v[120:123], v[140:143], v[180:183], v[120:123]
	v_mfma_f32_16x16x32_bf16 v[108:111], v[132:135], v[194:197], v[108:111]
	v_mfma_f32_16x16x32_bf16 v[104:107], v[140:143], v[194:197], v[104:107]
	v_mfma_f32_16x16x32_bf16 v[92:95], v[132:135], v[202:205], v[92:95]
	v_mfma_f32_16x16x32_bf16 v[88:91], v[140:143], v[202:205], v[88:91]
	v_mfma_f32_16x16x32_bf16 v[76:79], v[132:135], v[210:213], v[76:79]
	v_mfma_f32_16x16x32_bf16 v[72:75], v[140:143], v[210:213], v[72:75]
	v_mfma_f32_16x16x32_bf16 v[116:119], v[144:147], v[160:163], v[116:119]
	v_mfma_f32_16x16x32_bf16 v[112:115], v[152:155], v[160:163], v[112:115]
	v_mfma_f32_16x16x32_bf16 v[100:103], v[144:147], v[190:193], v[100:103]
	v_mfma_f32_16x16x32_bf16 v[96:99], v[152:155], v[190:193], v[96:99]
	v_mfma_f32_16x16x32_bf16 v[84:87], v[144:147], v[198:201], v[84:87]
	v_mfma_f32_16x16x32_bf16 v[80:83], v[152:155], v[198:201], v[80:83]
	v_mfma_f32_16x16x32_bf16 v[68:71], v[144:147], v[206:209], v[68:71]
	v_mfma_f32_16x16x32_bf16 v[64:67], v[152:155], v[206:209], v[64:67]
	v_mfma_f32_16x16x32_bf16 v[116:119], v[148:151], v[180:183], v[116:119]
	v_mfma_f32_16x16x32_bf16 v[112:115], v[156:159], v[180:183], v[112:115]
	v_mfma_f32_16x16x32_bf16 v[100:103], v[148:151], v[194:197], v[100:103]
	v_mfma_f32_16x16x32_bf16 v[96:99], v[156:159], v[194:197], v[96:99]
	v_mfma_f32_16x16x32_bf16 v[84:87], v[148:151], v[202:205], v[84:87]
	v_mfma_f32_16x16x32_bf16 v[80:83], v[156:159], v[202:205], v[80:83]
	v_mfma_f32_16x16x32_bf16 v[68:71], v[148:151], v[210:213], v[68:71]
	v_mfma_f32_16x16x32_bf16 v[64:67], v[156:159], v[210:213], v[64:67]
	s_barrier
	s_add_i32 s69, s57, s33
	v_lshl_add_u64 v[214:215], s[44:45], 0, v[168:169]
	s_mov_b32 m0, s69
	ds_read_b128 v[160:163], v189 offset:16384
	ds_read_b128 v[180:183], v189 offset:17408
	ds_read_b128 v[190:193], v189 offset:18432
	ds_read_b128 v[194:197], v189 offset:19456
	ds_read_b128 v[198:201], v189 offset:20480
	ds_read_b128 v[202:205], v189 offset:21504
	ds_read_b128 v[206:209], v189 offset:22528
	ds_read_b128 v[210:213], v189 offset:23552
	global_load_lds_dwordx4 v[214:215], off
	s_add_i32 m0, s69, 0x2000
	s_add_u32 s70, s44, 0x80000
	v_lshl_add_u64 v[216:217], s[44:45], 0, v[172:173]
	s_addc_u32 s71, s45, 0
	s_add_i32 s69, s58, s33
	global_load_lds_dwordx4 v[216:217], off
	v_lshl_add_u64 v[218:219], s[70:71], 0, v[168:169]
	s_mov_b32 m0, s69
	v_lshl_add_u64 v[220:221], s[46:47], 0, v[170:171]
	global_load_lds_dwordx4 v[218:219], off
	v_lshl_add_u64 v[218:219], s[70:71], 0, v[172:173]
	s_add_i32 m0, s69, 0x2000
	s_nop 0
	global_load_lds_dwordx4 v[218:219], off
	v_lshl_add_u64 v[218:219], s[46:47], 0, v[166:167]
	s_mov_b32 m0, s35
	s_nop 0
	global_load_lds_dwordx4 v[218:219], off
	s_mov_b32 m0, s43
	s_nop 0
	global_load_lds_dwordx4 v[220:221], off
	s_waitcnt vmcnt(8)
	s_waitcnt lgkmcnt(0)
	s_barrier
; #define PG8_STAGE(bufoff, gbase, voff) do { _Pragma("unroll") for (int _i = 0; _i < 2; ++_i) \
;         __builtin_amdgcn_global_load_lds((const unsigned*)((const char*)(gbase) + (voff)[_i]), (LAS unsigned*)(lds + (bufoff) + ldsw + _i * 8192), 16, 0, 0); } while (0)
; #define PG8_LDA(dst, b, h) do { _Pragma("unroll") for (int m = 0; m < 4; ++m) _Pragma("unroll") for (int k = 0; k < 2; ++k) dst[m][k] = *(const LAS bf16x8*)(lds + PG8_SA(b, h) + aoff + m * 2048 + k * 1024); } while (0)
; #define PG8_LDB(dst, b, h) do { _Pragma("unroll") for (int n = 0; n < 2; ++n) _Pragma("unroll") for (int k = 0; k < 2; ++k) dst[n][k] = *(const LAS bf16x8*)(lds + PG8_SB(b, h) + boff + n * 2048 + k * 1024); } while (0)
; #define PG8_MMA(ai, bj, At, Bt) do { __builtin_amdgcn_s_setprio(1); _Pragma("unroll") for (int m = 0; m < 4; ++m) _Pragma("unroll") for (int n = 0; n < 2; ++n) _Pragma("unroll") for (int k = 0; k < 2; ++k) \
;         acc[ai][bj][m][n] = __builtin_amdgcn_mfma_f32_16x16x32_bf16(Bt[n][k], At[m][k], acc[ai][bj][m][n], 0, 0, 0); __builtin_amdgcn_s_setprio(0); } while (0)
; #define PG8_WAIT_V(n) asm volatile("s_waitcnt vmcnt(" #n ")" ::: "memory")
; #define PG8_WAIT_L(n) asm volatile("s_waitcnt lgkmcnt(" #n ")" ::: "memory")
; #define PG8_BAR __builtin_amdgcn_s_barrier()
; #define PG8_SCHED __builtin_amdgcn_sched_barrier(0)
; template <class Epi, bool ALIGN_EPI = false, bool SP2 = true>
; __device__ __forceinline__ void gemm_phase(LAS unsigned char* lds, const Gemm g, const StaticOrder& S, const Epi& E) {
;     ...
;             PG8_WAIT_V(8); PG8_WAIT_L(0); PG8_BAR; PG8_MMA(1, 0, At, B0); PG8_MMA(1, 1, At, B1); PG8_BAR; PG8_SCHED;
;             PG8_LDB(B0, 1, 0); PG8_LDB(B1, 1, 1); PG8_SCHED; PG8_LDA(At, 1, 0); PG8_STAGE(PG8_SA(0, 1), a2 + hstep, voffA);
;             PG8_WAIT_V(8); PG8_WAIT_L(0); PG8_BAR; PG8_MMA(0, 0, At, B0); PG8_MMA(0, 1, At, B1); PG8_BAR; PG8_SCHED;
	s_waitcnt lgkmcnt(0)
	v_mfma_f32_16x16x32_bf16 v[60:63], v[128:131], v[160:163], v[60:63]
	v_mfma_f32_16x16x32_bf16 v[56:59], v[136:139], v[160:163], v[56:59]
	v_mfma_f32_16x16x32_bf16 v[44:47], v[128:131], v[190:193], v[44:47]
	v_mfma_f32_16x16x32_bf16 v[40:43], v[136:139], v[190:193], v[40:43]
	v_mfma_f32_16x16x32_bf16 v[28:31], v[128:131], v[198:201], v[28:31]
	v_mfma_f32_16x16x32_bf16 v[24:27], v[136:139], v[198:201], v[24:27]
	v_mfma_f32_16x16x32_bf16 v[12:15], v[128:131], v[206:209], v[12:15]
	v_mfma_f32_16x16x32_bf16 v[8:11], v[136:139], v[206:209], v[8:11]
	v_mfma_f32_16x16x32_bf16 v[60:63], v[132:135], v[180:183], v[60:63]
	v_mfma_f32_16x16x32_bf16 v[56:59], v[140:143], v[180:183], v[56:59]
	v_mfma_f32_16x16x32_bf16 v[44:47], v[132:135], v[194:197], v[44:47]
	v_mfma_f32_16x16x32_bf16 v[40:43], v[140:143], v[194:197], v[40:43]
	v_mfma_f32_16x16x32_bf16 v[28:31], v[132:135], v[202:205], v[28:31]
	v_mfma_f32_16x16x32_bf16 v[24:27], v[140:143], v[202:205], v[24:27]
	v_mfma_f32_16x16x32_bf16 v[12:15], v[132:135], v[210:213], v[12:15]
	v_mfma_f32_16x16x32_bf16 v[8:11], v[140:143], v[210:213], v[8:11]
	v_mfma_f32_16x16x32_bf16 v[52:55], v[144:147], v[160:163], v[52:55]
	v_mfma_f32_16x16x32_bf16 v[48:51], v[152:155], v[160:163], v[48:51]
	v_mfma_f32_16x16x32_bf16 v[36:39], v[144:147], v[190:193], v[36:39]
	v_mfma_f32_16x16x32_bf16 v[32:35], v[152:155], v[190:193], v[32:35]
	v_mfma_f32_16x16x32_bf16 v[20:23], v[144:147], v[198:201], v[20:23]
	v_mfma_f32_16x16x32_bf16 v[16:19], v[152:155], v[198:201], v[16:19]
	v_mfma_f32_16x16x32_bf16 v[4:7], v[144:147], v[206:209], v[4:7]
	v_mfma_f32_16x16x32_bf16 v[0:3], v[152:155], v[206:209], v[0:3]
	v_mfma_f32_16x16x32_bf16 v[52:55], v[148:151], v[180:183], v[52:55]
	v_mfma_f32_16x16x32_bf16 v[48:51], v[156:159], v[180:183], v[48:51]
	v_mfma_f32_16x16x32_bf16 v[36:39], v[148:151], v[194:197], v[36:39]
	v_mfma_f32_16x16x32_bf16 v[32:35], v[156:159], v[194:197], v[32:35]
	v_mfma_f32_16x16x32_bf16 v[20:23], v[148:151], v[202:205], v[20:23]
	v_mfma_f32_16x16x32_bf16 v[16:19], v[156:159], v[202:205], v[16:19]
	v_mfma_f32_16x16x32_bf16 v[4:7], v[148:151], v[210:213], v[4:7]
	v_mfma_f32_16x16x32_bf16 v[0:3], v[156:159], v[210:213], v[0:3]
	s_barrier
	s_add_i32 s69, 0, 0x18000
	s_add_i32 s70, 0, 0x1c000
	v_add_u32_e32 v140, s69, v185
	v_add_u32_e32 v156, s70, v185
	ds_read_b128 v[128:131], v140
	ds_read_b128 v[132:135], v140 offset:1024
	ds_read_b128 v[136:139], v140 offset:2048
	ds_read_b128 v[140:143], v140 offset:3072
	ds_read_b128 v[144:147], v156
	ds_read_b128 v[148:151], v156 offset:1024
	ds_read_b128 v[152:155], v156 offset:2048
	ds_read_b128 v[156:159], v156 offset:3072
	s_add_u32 s46, s46, 0x80000
	s_addc_u32 s47, s47, 0
	s_mov_b32 m0, s48
	v_lshl_add_u64 v[222:223], s[46:47], 0, v[166:167]
	ds_read_b128 v[160:163], v189 offset:32768
	ds_read_b128 v[180:183], v189 offset:33792
	ds_read_b128 v[190:193], v189 offset:34816
	ds_read_b128 v[194:197], v189 offset:35840
	ds_read_b128 v[198:201], v189 offset:36864
	ds_read_b128 v[202:205], v189 offset:37888
	ds_read_b128 v[206:209], v189 offset:38912
	ds_read_b128 v[210:213], v189 offset:39936
	global_load_lds_dwordx4 v[222:223], off
	v_lshl_add_u64 v[222:223], s[46:47], 0, v[170:171]
	s_mov_b32 m0, s49
	s_nop 0
	global_load_lds_dwordx4 v[222:223], off
	s_waitcnt vmcnt(8)
	s_waitcnt lgkmcnt(0)
	s_barrier
	s_waitcnt lgkmcnt(0)
	v_mfma_f32_16x16x32_bf16 v[124:127], v[128:131], v[160:163], v[124:127]
	v_mfma_f32_16x16x32_bf16 v[120:123], v[136:139], v[160:163], v[120:123]
	v_mfma_f32_16x16x32_bf16 v[108:111], v[128:131], v[190:193], v[108:111]
	v_mfma_f32_16x16x32_bf16 v[104:107], v[136:139], v[190:193], v[104:107]
	v_mfma_f32_16x16x32_bf16 v[92:95], v[128:131], v[198:201], v[92:95]
	v_mfma_f32_16x16x32_bf16 v[88:91], v[136:139], v[198:201], v[88:91]
	v_mfma_f32_16x16x32_bf16 v[76:79], v[128:131], v[206:209], v[76:79]
	v_mfma_f32_16x16x32_bf16 v[72:75], v[136:139], v[206:209], v[72:75]
	v_mfma_f32_16x16x32_bf16 v[124:127], v[132:135], v[180:183], v[124:127]
	v_mfma_f32_16x16x32_bf16 v[120:123], v[140:143], v[180:183], v[120:123]
	v_mfma_f32_16x16x32_bf16 v[108:111], v[132:135], v[194:197], v[108:111]
	v_mfma_f32_16x16x32_bf16 v[104:107], v[140:143], v[194:197], v[104:107]
	v_mfma_f32_16x16x32_bf16 v[92:95], v[132:135], v[202:205], v[92:95]
	v_mfma_f32_16x16x32_bf16 v[88:91], v[140:143], v[202:205], v[88:91]
	v_mfma_f32_16x16x32_bf16 v[76:79], v[132:135], v[210:213], v[76:79]
	v_mfma_f32_16x16x32_bf16 v[72:75], v[140:143], v[210:213], v[72:75]
	v_mfma_f32_16x16x32_bf16 v[116:119], v[144:147], v[160:163], v[116:119]
	v_mfma_f32_16x16x32_bf16 v[112:115], v[152:155], v[160:163], v[112:115]
	v_mfma_f32_16x16x32_bf16 v[100:103], v[144:147], v[190:193], v[100:103]
	v_mfma_f32_16x16x32_bf16 v[96:99], v[152:155], v[190:193], v[96:99]
	v_mfma_f32_16x16x32_bf16 v[84:87], v[144:147], v[198:201], v[84:87]
	v_mfma_f32_16x16x32_bf16 v[80:83], v[152:155], v[198:201], v[80:83]
	v_mfma_f32_16x16x32_bf16 v[68:71], v[144:147], v[206:209], v[68:71]
	v_mfma_f32_16x16x32_bf16 v[64:67], v[152:155], v[206:209], v[64:67]
	v_mfma_f32_16x16x32_bf16 v[116:119], v[148:151], v[180:183], v[116:119]
	v_mfma_f32_16x16x32_bf16 v[112:115], v[156:159], v[180:183], v[112:115]
	v_mfma_f32_16x16x32_bf16 v[100:103], v[148:151], v[194:197], v[100:103]
	v_mfma_f32_16x16x32_bf16 v[96:99], v[156:159], v[194:197], v[96:99]
	v_mfma_f32_16x16x32_bf16 v[84:87], v[148:151], v[202:205], v[84:87]
	v_mfma_f32_16x16x32_bf16 v[80:83], v[156:159], v[202:205], v[80:83]
	v_mfma_f32_16x16x32_bf16 v[68:71], v[148:151], v[210:213], v[68:71]
	v_mfma_f32_16x16x32_bf16 v[64:67], v[156:159], v[210:213], v[64:67]
	s_barrier
; #define PG8_STAGE(bufoff, gbase, voff) do { _Pragma("unroll") for (int _i = 0; _i < 2; ++_i) \
;         __builtin_amdgcn_global_load_lds((const unsigned*)((const char*)(gbase) + (voff)[_i]), (LAS unsigned*)(lds + (bufoff) + ldsw + _i * 8192), 16, 0, 0); } while (0)
; #define PG8_LDA(dst, b, h) do { _Pragma("unroll") for (int m = 0; m < 4; ++m) _Pragma("unroll") for (int k = 0; k < 2; ++k) dst[m][k] = *(const LAS bf16x8*)(lds + PG8_SA(b, h) + aoff + m * 2048 + k * 1024); } while (0)
; #define PG8_MMA(ai, bj, At, Bt) do { __builtin_amdgcn_s_setprio(1); _Pragma("unroll") for (int m = 0; m < 4; ++m) _Pragma("unroll") for (int n = 0; n < 2; ++n) _Pragma("unroll") for (int k = 0; k < 2; ++k) \
;         acc[ai][bj][m][n] = __builtin_amdgcn_mfma_f32_16x16x32_bf16(Bt[n][k], At[m][k], acc[ai][bj][m][n], 0, 0, 0); __builtin_amdgcn_s_setprio(0); } while (0)
; #define PG8_WAIT_V(n) asm volatile("s_waitcnt vmcnt(" #n ")" ::: "memory")
; #define PG8_WAIT_L(n) asm volatile("s_waitcnt lgkmcnt(" #n ")" ::: "memory")
; #define PG8_BAR __builtin_amdgcn_s_barrier()
; #define PG8_SCHED __builtin_amdgcn_sched_barrier(0)
; template <class Epi, bool ALIGN_EPI = false, bool SP2 = true>
; __device__ __forceinline__ void gemm_phase(LAS unsigned char* lds, const Gemm g, const StaticOrder& S, const Epi& E) {
;     ...
;             PG8_LDA(At, 1, 1); PG8_STAGE(PG8_SB(1, 0), b3, voffB); PG8_STAGE(PG8_SB(1, 1), b3 + hstep, voffB); PG8_STAGE(PG8_SA(1, 0), a3, voffA);
;             PG8_WAIT_V(8); PG8_WAIT_L(0); PG8_BAR; PG8_MMA(1, 0, At, B0); PG8_MMA(1, 1, At, B1); PG8_BAR; PG8_SCHED;
;     ...
;         if constexpr (ALIGN_EPI) { if (wr == 0) PG8_BAR; }
	s_add_i32 s46, s69, s33
	v_lshl_add_u64 v[214:215], v[214:215], 0, s[8:9]
	s_mov_b32 m0, s46
	ds_read_b128 v[160:163], v189 offset:49152
	ds_read_b128 v[180:183], v189 offset:50176
	ds_read_b128 v[190:193], v189 offset:51200
	ds_read_b128 v[194:197], v189 offset:52224
	ds_read_b128 v[198:201], v189 offset:53248
	ds_read_b128 v[202:205], v189 offset:54272
	ds_read_b128 v[206:209], v189 offset:55296
	ds_read_b128 v[210:213], v189 offset:56320
	global_load_lds_dwordx4 v[214:215], off
	s_add_i32 m0, s46, 0x2000
	s_add_u32 s44, s44, 0x80080
	v_lshl_add_u64 v[214:215], v[216:217], 0, s[8:9]
	s_addc_u32 s45, s45, 0
	s_add_i32 s46, s70, s33
	global_load_lds_dwordx4 v[214:215], off
	v_lshl_add_u64 v[214:215], s[44:45], 0, v[168:169]
	s_mov_b32 m0, s46
	s_nop 0
	global_load_lds_dwordx4 v[214:215], off
	v_lshl_add_u64 v[214:215], s[44:45], 0, v[172:173]
	s_add_i32 m0, s46, 0x2000
	s_nop 0
	global_load_lds_dwordx4 v[214:215], off
	v_lshl_add_u64 v[214:215], v[218:219], 0, s[8:9]
	s_mov_b32 m0, s54
	s_nop 0
	global_load_lds_dwordx4 v[214:215], off
	v_lshl_add_u64 v[214:215], v[220:221], 0, s[8:9]
	s_mov_b32 m0, s55
	s_nop 0
	global_load_lds_dwordx4 v[214:215], off
	s_waitcnt vmcnt(8)
	s_waitcnt lgkmcnt(0)
	s_barrier
	s_waitcnt lgkmcnt(0)
	v_mfma_f32_16x16x32_bf16 v[60:63], v[128:131], v[160:163], v[60:63]
	v_mfma_f32_16x16x32_bf16 v[56:59], v[136:139], v[160:163], v[56:59]
	v_mfma_f32_16x16x32_bf16 v[44:47], v[128:131], v[190:193], v[44:47]
	v_mfma_f32_16x16x32_bf16 v[40:43], v[136:139], v[190:193], v[40:43]
	v_mfma_f32_16x16x32_bf16 v[28:31], v[128:131], v[198:201], v[28:31]
	v_mfma_f32_16x16x32_bf16 v[24:27], v[136:139], v[198:201], v[24:27]
	v_mfma_f32_16x16x32_bf16 v[12:15], v[128:131], v[206:209], v[12:15]
	v_mfma_f32_16x16x32_bf16 v[8:11], v[136:139], v[206:209], v[8:11]
	v_mfma_f32_16x16x32_bf16 v[60:63], v[132:135], v[180:183], v[60:63]
	v_mfma_f32_16x16x32_bf16 v[56:59], v[140:143], v[180:183], v[56:59]
	v_mfma_f32_16x16x32_bf16 v[44:47], v[132:135], v[194:197], v[44:47]
	v_mfma_f32_16x16x32_bf16 v[40:43], v[140:143], v[194:197], v[40:43]
	v_mfma_f32_16x16x32_bf16 v[28:31], v[132:135], v[202:205], v[28:31]
	v_mfma_f32_16x16x32_bf16 v[24:27], v[140:143], v[202:205], v[24:27]
	v_mfma_f32_16x16x32_bf16 v[12:15], v[132:135], v[210:213], v[12:15]
	v_mfma_f32_16x16x32_bf16 v[8:11], v[140:143], v[210:213], v[8:11]
	v_mfma_f32_16x16x32_bf16 v[52:55], v[144:147], v[160:163], v[52:55]
	v_mfma_f32_16x16x32_bf16 v[48:51], v[152:155], v[160:163], v[48:51]
	v_mfma_f32_16x16x32_bf16 v[36:39], v[144:147], v[190:193], v[36:39]
	v_mfma_f32_16x16x32_bf16 v[32:35], v[152:155], v[190:193], v[32:35]
	v_mfma_f32_16x16x32_bf16 v[20:23], v[144:147], v[198:201], v[20:23]
	v_mfma_f32_16x16x32_bf16 v[16:19], v[152:155], v[198:201], v[16:19]
	v_mfma_f32_16x16x32_bf16 v[4:7], v[144:147], v[206:209], v[4:7]
	v_mfma_f32_16x16x32_bf16 v[0:3], v[152:155], v[206:209], v[0:3]
	v_mfma_f32_16x16x32_bf16 v[52:55], v[148:151], v[180:183], v[52:55]
	v_mfma_f32_16x16x32_bf16 v[48:51], v[156:159], v[180:183], v[48:51]
	v_mfma_f32_16x16x32_bf16 v[36:39], v[148:151], v[194:197], v[36:39]
	v_mfma_f32_16x16x32_bf16 v[32:35], v[156:159], v[194:197], v[32:35]
	v_mfma_f32_16x16x32_bf16 v[20:23], v[148:151], v[202:205], v[20:23]
	v_mfma_f32_16x16x32_bf16 v[16:19], v[156:159], v[202:205], v[16:19]
	v_mfma_f32_16x16x32_bf16 v[4:7], v[148:151], v[210:213], v[4:7]
	v_mfma_f32_16x16x32_bf16 v[0:3], v[156:159], v[210:213], v[0:3]
	s_add_i32 s68, s68, 2
	s_add_u32 s40, s40, 0x100
	s_addc_u32 s41, s41, 0
	s_add_u32 s66, s66, 0x100
	s_addc_u32 s67, s67, 0
	s_cmp_gt_u32 s68, 29
	s_barrier
	s_cbranch_scc0 .LBB0_855
	s_and_b64 vcc, exec, s[10:11]
	s_cbranch_vccz .LBB0_858
	s_barrier
